# speedup vs baseline: 1.0117x; 1.0117x over previous
; #define PG8_STAGE(bufoff, gbase, voff) do { _Pragma("unroll") for (int _i = 0; _i < 2; ++_i) \
;         __builtin_amdgcn_global_load_lds((const unsigned*)((const char*)(gbase) + (voff)[_i]), (PG8_LAS unsigned*)(lds + (bufoff) + ldsw + _i * 8192), 16, 0, 0); } while (0)
; #define PG8_WAIT_V(n) asm volatile("s_waitcnt vmcnt(" #n ")" ::: "memory")
; #define PG8_BAR __builtin_amdgcn_s_barrier()
; template <class Epi, class Sched, bool ALIGN_EPI = false, bool SP2 = false>
; __device__ __forceinline__ void gemm_phase(PG8_LAS unsigned char* lds, const Gemm g, const Sched& S, const Epi& E) {
;     ...
;         PG8_STAGE(PG8_SB(0, 0), cB, voffB); PG8_STAGE(PG8_SB(0, 1), cB + hstep, voffB); PG8_STAGE(PG8_SA(0, 0), cA, voffA); PG8_STAGE(PG8_SA(0, 1), cA + hstep, voffA);
;         if (wr == 1) PG8_BAR;
;         PG8_WAIT_V(2); PG8_BAR;
;         PG8_STAGE(PG8_SB(1, 0), cB + kstep, voffB); PG8_STAGE(PG8_SA(1, 0), cA + kstep, voffA); PG8_STAGE(PG8_SB(1, 1), cB + hstep + kstep, voffB);
;         PG8_WAIT_V(6); PG8_BAR;
.LBB0_199:
	v_bfe_u32 v16, v9, 4, 2
	v_and_b32_e32 v15, 15, v9
	v_lshlrev_b32_e32 v17, 4, v16
	v_lshlrev_b32_e32 v9, 2, v9
	v_lshl_or_b32 v237, s4, 6, v15
	v_lshl_or_b32 v15, v15, 6, v17
	s_lshl_b32 s4, s4, 13
	v_and_b32_e32 v9, 32, v9
	v_bitop3_b32 v17, v15, s4, v9 bitop3:0xde
	s_lshl_b32 s4, s5, 5
	s_and_b32 s6, s4, 0x60
	s_add_i32 m0, s67, 0x18000
	v_lshl_add_u64 v[6:7], v[6:7], 0, s[90:91]
	s_lshl_b32 s4, s6, 7
	s_waitcnt vmcnt(2)
	s_barrier
	global_load_lds_dwordx4 v[6:7], off
	v_lshl_add_u64 v[4:5], v[4:5], 0, s[90:91]
	s_add_i32 m0, s67, 0x1a000
	s_add_i32 s79, s67, 0x8000
	s_add_i32 s80, s67, 0xa000
	v_bitop3_b32 v238, v15, s4, v9 bitop3:0xde
	global_load_lds_dwordx4 v[4:5], off
	v_lshl_add_u64 v[0:1], v[0:1], 0, s[90:91]
	s_mov_b32 m0, s79
	s_add_u32 s4, s70, 0x80080
	global_load_lds_dwordx4 v[0:1], off
	v_lshl_add_u64 v[0:1], v[2:3], 0, s[90:91]
	s_mov_b32 m0, s80
	s_addc_u32 s5, s71, 0
	global_load_lds_dwordx4 v[0:1], off
	s_add_i32 m0, s67, 0x1c000
	v_lshl_add_u64 v[0:1], s[4:5], 0, v[188:189]
	global_load_lds_dwordx4 v[0:1], off
	v_lshl_add_u64 v[0:1], s[4:5], 0, v[194:195]
	s_add_i32 m0, s67, 0x1e000
	s_cmpk_lt_u32 s3, 0x100
	global_load_lds_dwordx4 v[0:1], off
	v_lshlrev_b32_e32 v0, 15, v8
	v_and_b32_e32 v0, 0xffff0000, v0
	v_lshl_add_u32 v0, v10, 12, v0
	v_and_b32_e32 v1, 1, v8
	v_lshl_or_b32 v0, v1, 6, v0
	v_lshl_add_u32 v196, v11, 1, v0
	v_lshlrev_b32_e32 v0, 15, v12
	v_and_b32_e32 v0, 0xffff0000, v0
	s_waitcnt vmcnt(0)
	v_lshl_add_u32 v0, v13, 12, v0
	v_and_b32_e32 v1, 1, v12
	v_lshl_or_b32 v0, v1, 6, v0
	s_cselect_b64 s[56:57], -1, 0
	s_mov_b32 s81, 0
	v_cmp_eq_u32_e64 s[4:5], 0, v16
	s_waitcnt lgkmcnt(0)
	s_ashr_i32 s86, s14, 31
	v_lshl_or_b32 v239, v16, 3, s6
	v_mov_b32_e32 v197, v189
	v_lshl_add_u32 v198, v14, 1, v0
	v_mov_b32_e32 v199, v189
	v_add_u32_e32 v240, 0, v17
	s_movk_i32 s43, 0x6000
	s_barrier
	s_branch .LBB0_202

; #define PG8_STAGE(bufoff, gbase, voff) do { _Pragma("unroll") for (int _i = 0; _i < 2; ++_i) \
;         __builtin_amdgcn_global_load_lds((const unsigned*)((const char*)(gbase) + (voff)[_i]), (PG8_LAS unsigned*)(lds + (bufoff) + ldsw + _i * 8192), 16, 0, 0); } while (0)
; #define PG8_LDA(dst, b, h) do { _Pragma("unroll") for (int m = 0; m < 4; ++m) _Pragma("unroll") for (int k = 0; k < 2; ++k) dst[m][k] = *(const PG8_LAS bf16x8*)(lds + PG8_SA(b, h) + aoff + m * 2048 + k * 1024); } while (0)
; #define PG8_LDB(dst, b, h) do { _Pragma("unroll") for (int n = 0; n < 2; ++n) _Pragma("unroll") for (int k = 0; k < 2; ++k) dst[n][k] = *(const PG8_LAS bf16x8*)(lds + PG8_SB(b, h) + boff + n * 2048 + k * 1024); } while (0)
; #define PG8_SCHED __builtin_amdgcn_sched_barrier(0)
; template <class Epi, class Sched, bool ALIGN_EPI = false, bool SP2 = false>
; __device__ __forceinline__ void gemm_phase(PG8_LAS unsigned char* lds, const Gemm g, const Sched& S, const Epi& E) {
;     ...
;         for (int t = 0; t < nt; t += 2) {
;             const bool last = (t == nt - 2);
;             const char* a1 = cA + (size_t)(t + 1) * kstep;
;             const char* a2 = last ? nA : cA + (size_t)(t + 2) * kstep; const char* b2 = last ? nB : cB + (size_t)(t + 2) * kstep;
;             const char* a3 = a2 + kstep; const char* b3 = b2 + kstep;
;             if (last && has_next) S.a_ready(nxt);
;             if constexpr (SP2) {
;             PG8_LDB(B0, 0, 0); PG8_LDB(B1, 0, 1); PG8_SCHED; PG8_LDA(At, 0, 0); PG8_STAGE(PG8_SA(1, 1), a1 + hstep, voffA);
;     ...
;         for (int a = 0; a < 2; ++a)
; #pragma unroll
;             for (int b = 0; b < 2; ++b)
; #pragma unroll
;                 for (int m = 0; m < 4; ++m)
; #pragma unroll
;                     for (int n = 0; n < 2; ++n) acc[a][b][m][n] = (f32x4){0.f, 0.f, 0.f, 0.f};
;         cur = nxt; cA = nA; cB = nB; ++ui;
.LBB0_204:
	s_ashr_i32 s61, s60, 31
	s_lshl_b64 s[36:37], s[60:61], 20
	s_add_u32 s62, s45, s36
	s_addc_u32 s63, s44, s37
	s_and_b64 s[36:37], s[6:7], exec
	s_cselect_b32 s9, s63, s69
	s_cselect_b32 s61, s62, s68
	s_ashr_i32 s59, s58, 31
	s_lshl_b64 s[36:37], s[58:59], 20
	s_add_u32 s64, s54, s36
	s_addc_u32 s65, s55, s37
	s_and_b64 s[36:37], s[6:7], exec
	s_cselect_b32 s59, s65, s71
	s_cselect_b32 s87, s64, s70
	s_add_u32 s68, s68, 0x80080
	s_addc_u32 s69, s69, 0
	s_add_u32 s3, s70, 0x100
	v_mov_b32_e32 v0, 0
	s_addc_u32 s88, s71, 0
	s_mov_b32 s89, -2
	v_mov_b32_e32 v1, v0
	v_mov_b32_e32 v2, v0
	v_mov_b32_e32 v3, v0
	v_mov_b32_e32 v4, v0
	v_mov_b32_e32 v5, v0
	v_mov_b32_e32 v6, v0
	v_mov_b32_e32 v7, v0
	v_mov_b32_e32 v16, v0
	v_mov_b32_e32 v17, v0
	v_mov_b32_e32 v18, v0
	v_mov_b32_e32 v19, v0
	v_mov_b32_e32 v20, v0
	v_mov_b32_e32 v21, v0
	v_mov_b32_e32 v22, v0
	v_mov_b32_e32 v23, v0
	v_mov_b32_e32 v32, v0
	v_mov_b32_e32 v33, v0
	v_mov_b32_e32 v34, v0
	v_mov_b32_e32 v35, v0
	v_mov_b32_e32 v36, v0
	v_mov_b32_e32 v37, v0
	v_mov_b32_e32 v38, v0
	v_mov_b32_e32 v39, v0
	v_mov_b32_e32 v48, v0
	v_mov_b32_e32 v49, v0
	v_mov_b32_e32 v50, v0
	v_mov_b32_e32 v51, v0
	v_mov_b32_e32 v52, v0
	v_mov_b32_e32 v53, v0
	v_mov_b32_e32 v54, v0
	v_mov_b32_e32 v55, v0
	v_mov_b32_e32 v8, v0
	v_mov_b32_e32 v9, v0
	v_mov_b32_e32 v10, v0
	v_mov_b32_e32 v11, v0
	v_mov_b32_e32 v12, v0
	v_mov_b32_e32 v13, v0
	v_mov_b32_e32 v14, v0
	v_mov_b32_e32 v15, v0
	v_mov_b32_e32 v24, v0
	v_mov_b32_e32 v25, v0
	v_mov_b32_e32 v26, v0
	v_mov_b32_e32 v27, v0
	v_mov_b32_e32 v28, v0
	v_mov_b32_e32 v29, v0
	v_mov_b32_e32 v30, v0
	v_mov_b32_e32 v31, v0
	v_mov_b32_e32 v40, v0
	v_mov_b32_e32 v41, v0
	v_mov_b32_e32 v42, v0
	v_mov_b32_e32 v43, v0
	v_mov_b32_e32 v44, v0
	v_mov_b32_e32 v45, v0
	v_mov_b32_e32 v46, v0
	v_mov_b32_e32 v47, v0
	v_mov_b32_e32 v56, v0
	v_mov_b32_e32 v57, v0
	v_mov_b32_e32 v58, v0
	v_mov_b32_e32 v59, v0
	v_mov_b32_e32 v60, v0
	v_mov_b32_e32 v61, v0
	v_mov_b32_e32 v62, v0
	v_mov_b32_e32 v63, v0
	v_mov_b32_e32 v64, v0
	v_mov_b32_e32 v65, v0
	v_mov_b32_e32 v66, v0
	v_mov_b32_e32 v67, v0
	s_nop 0
	v_mov_b32_e32 v68, v0
	v_mov_b32_e32 v69, v0
	v_mov_b32_e32 v70, v0
	v_mov_b32_e32 v71, v0
	v_mov_b32_e32 v84, v0
	v_mov_b32_e32 v85, v0
	v_mov_b32_e32 v86, v0
	v_mov_b32_e32 v87, v0
	v_mov_b32_e32 v92, v0
	v_mov_b32_e32 v93, v0
	v_mov_b32_e32 v94, v0
	v_mov_b32_e32 v95, v0
	v_mov_b32_e32 v112, v0
	v_mov_b32_e32 v113, v0
	v_mov_b32_e32 v114, v0
	v_mov_b32_e32 v115, v0
	v_mov_b32_e32 v116, v0
	v_mov_b32_e32 v117, v0
	v_mov_b32_e32 v118, v0
	v_mov_b32_e32 v119, v0
	v_mov_b32_e32 v136, v0
	v_mov_b32_e32 v137, v0
	v_mov_b32_e32 v138, v0
	v_mov_b32_e32 v139, v0
	v_mov_b32_e32 v140, v0
	v_mov_b32_e32 v141, v0
	v_mov_b32_e32 v142, v0
	v_mov_b32_e32 v143, v0
	v_mov_b32_e32 v72, v0
	v_mov_b32_e32 v73, v0
	v_mov_b32_e32 v74, v0
	v_mov_b32_e32 v75, v0
	v_mov_b32_e32 v76, v0
	v_mov_b32_e32 v77, v0
	v_mov_b32_e32 v78, v0
	v_mov_b32_e32 v79, v0
	v_mov_b32_e32 v96, v0
	v_mov_b32_e32 v97, v0
	v_mov_b32_e32 v98, v0
	v_mov_b32_e32 v99, v0
	v_mov_b32_e32 v100, v0
	v_mov_b32_e32 v101, v0
	v_mov_b32_e32 v102, v0
	v_mov_b32_e32 v103, v0
	v_mov_b32_e32 v120, v0
	v_mov_b32_e32 v121, v0
	v_mov_b32_e32 v122, v0
	v_mov_b32_e32 v123, v0
	v_mov_b32_e32 v124, v0
	v_mov_b32_e32 v125, v0
	v_mov_b32_e32 v126, v0
	v_mov_b32_e32 v127, v0
	v_mov_b32_e32 v144, v0
	v_mov_b32_e32 v145, v0
	v_mov_b32_e32 v146, v0
	v_mov_b32_e32 v147, v0
	v_mov_b32_e32 v148, v0
	v_mov_b32_e32 v149, v0
	v_mov_b32_e32 v150, v0
	v_mov_b32_e32 v151, v0
	s_waitcnt vmcnt(16)
	v_add_u32_e32 v204, 0x10000, v238
.LBB0_205:
	s_add_u32 s36, s68, 0xfff80080
	s_addc_u32 s37, s69, -1
	s_add_i32 s38, 0, 0x10000
	s_cmp_eq_u32 s89, 28
	s_cselect_b32 s73, s9, s37
	s_cselect_b32 s72, s61, s36
	s_cselect_b32 s71, s59, s88
	s_cselect_b32 s70, s87, s3
	s_add_i32 s39, 0, 0x14000
	ds_read_b128 v[80:83], v204
	ds_read_b128 v[88:91], v204 offset:1024
	ds_read_b128 v[104:107], v204 offset:2048
	ds_read_b128 v[108:111], v204 offset:3072
	ds_read_b128 v[128:131], v204 offset:16384
	ds_read_b128 v[132:135], v204 offset:17408
	ds_read_b128 v[152:155], v204 offset:18432
	ds_read_b128 v[156:159], v204 offset:19456
	s_add_i32 m0, s67, 0xc000
	ds_read_b128 v[160:163], v240
	ds_read_b128 v[164:167], v240 offset:1024
	ds_read_b128 v[168:171], v240 offset:2048
	ds_read_b128 v[172:175], v240 offset:3072
	ds_read_b128 v[176:179], v240 offset:4096
	ds_read_b128 v[180:183], v240 offset:5120
	ds_read_b128 v[184:187], v240 offset:6144
	ds_read_b128 v[200:203], v240 offset:7168
	global_load_lds_dwordx4 v196, s[68:69]
	s_add_i32 m0, s67, 0xe000
	s_nop 0
	global_load_lds_dwordx4 v198, s[68:69]
	s_cmp_eq_u32 s89, -2
	s_cbranch_scc1 .Lew_first_205_0
	s_waitcnt vmcnt(8)
; #define PG8_STAGE(bufoff, gbase, voff) do { _Pragma("unroll") for (int _i = 0; _i < 2; ++_i) \
;         __builtin_amdgcn_global_load_lds((const unsigned*)((const char*)(gbase) + (voff)[_i]), (PG8_LAS unsigned*)(lds + (bufoff) + ldsw + _i * 8192), 16, 0, 0); } while (0)
; #define PG8_LDA(dst, b, h) do { _Pragma("unroll") for (int m = 0; m < 4; ++m) _Pragma("unroll") for (int k = 0; k < 2; ++k) dst[m][k] = *(const PG8_LAS bf16x8*)(lds + PG8_SA(b, h) + aoff + m * 2048 + k * 1024); } while (0)
; #define PG8_LDB(dst, b, h) do { _Pragma("unroll") for (int n = 0; n < 2; ++n) _Pragma("unroll") for (int k = 0; k < 2; ++k) dst[n][k] = *(const PG8_LAS bf16x8*)(lds + PG8_SB(b, h) + boff + n * 2048 + k * 1024); } while (0)
; #define PG8_MMA(ai, bj, At, Bt) do { __builtin_amdgcn_s_setprio(1); _Pragma("unroll") for (int m = 0; m < 4; ++m) _Pragma("unroll") for (int n = 0; n < 2; ++n) _Pragma("unroll") for (int k = 0; k < 2; ++k) \
;         acc[ai][bj][m][n] = __builtin_amdgcn_mfma_f32_16x16x32_bf16(Bt[n][k], At[m][k], acc[ai][bj][m][n], 0, 0, 0); __builtin_amdgcn_s_setprio(0); } while (0)
; #define PG8_WAIT_V(n) asm volatile("s_waitcnt vmcnt(" #n ")" ::: "memory")
; #define PG8_WAIT_L(n) asm volatile("s_waitcnt lgkmcnt(" #n ")" ::: "memory")
; #define PG8_BAR __builtin_amdgcn_s_barrier()
; #define PG8_SCHED __builtin_amdgcn_sched_barrier(0)
; template <class Epi, class Sched, bool ALIGN_EPI = false, bool SP2 = false>
; __device__ __forceinline__ void gemm_phase(PG8_LAS unsigned char* lds, const Gemm g, const Sched& S, const Epi& E) {
;     ...
;             PG8_LDB(B0, 0, 0); PG8_LDB(B1, 0, 1); PG8_SCHED; PG8_LDA(At, 0, 0); PG8_STAGE(PG8_SA(1, 1), a1 + hstep, voffA);
;             PG8_WAIT_V(8); PG8_WAIT_L(0); PG8_BAR; PG8_MMA(0, 0, At, B0); PG8_MMA(0, 1, At, B1); PG8_BAR; PG8_SCHED;
;             PG8_LDA(At, 0, 1); PG8_STAGE(PG8_SB(0, 0), b2, voffB); PG8_STAGE(PG8_SB(0, 1), b2 + hstep, voffB); PG8_STAGE(PG8_SA(0, 0), a2, voffA);
;             PG8_WAIT_V(8); PG8_WAIT_L(0); PG8_BAR; PG8_MMA(1, 0, At, B0); PG8_MMA(1, 1, At, B1); PG8_BAR; PG8_SCHED;
.Lew_join_205_0:
	s_waitcnt lgkmcnt(0)
	s_barrier
	s_setprio 1
	s_waitcnt lgkmcnt(0)
	v_mfma_f32_16x16x32_bf16 v[148:151], v[80:83], v[160:163], v[148:151]
	v_mfma_f32_16x16x32_bf16 v[148:151], v[88:91], v[164:167], v[148:151]
	v_mfma_f32_16x16x32_bf16 v[144:147], v[104:107], v[160:163], v[144:147]
	v_mfma_f32_16x16x32_bf16 v[144:147], v[108:111], v[164:167], v[144:147]
	v_mfma_f32_16x16x32_bf16 v[124:127], v[80:83], v[168:171], v[124:127]
	v_mfma_f32_16x16x32_bf16 v[124:127], v[88:91], v[172:175], v[124:127]
	v_mfma_f32_16x16x32_bf16 v[120:123], v[104:107], v[168:171], v[120:123]
	v_mfma_f32_16x16x32_bf16 v[120:123], v[108:111], v[172:175], v[120:123]
	v_mfma_f32_16x16x32_bf16 v[100:103], v[80:83], v[176:179], v[100:103]
	v_mfma_f32_16x16x32_bf16 v[100:103], v[88:91], v[180:183], v[100:103]
	v_mfma_f32_16x16x32_bf16 v[96:99], v[104:107], v[176:179], v[96:99]
	v_mfma_f32_16x16x32_bf16 v[96:99], v[108:111], v[180:183], v[96:99]
	v_mfma_f32_16x16x32_bf16 v[76:79], v[80:83], v[184:187], v[76:79]
	v_mfma_f32_16x16x32_bf16 v[76:79], v[88:91], v[200:203], v[76:79]
	v_mfma_f32_16x16x32_bf16 v[72:75], v[104:107], v[184:187], v[72:75]
	v_mfma_f32_16x16x32_bf16 v[72:75], v[108:111], v[200:203], v[72:75]
	s_setprio 0
	s_setprio 1
	v_mfma_f32_16x16x32_bf16 v[140:143], v[128:131], v[160:163], v[140:143]
	v_mfma_f32_16x16x32_bf16 v[140:143], v[132:135], v[164:167], v[140:143]
	v_mfma_f32_16x16x32_bf16 v[136:139], v[152:155], v[160:163], v[136:139]
	v_mfma_f32_16x16x32_bf16 v[136:139], v[156:159], v[164:167], v[136:139]
	v_mfma_f32_16x16x32_bf16 v[116:119], v[128:131], v[168:171], v[116:119]
	v_mfma_f32_16x16x32_bf16 v[116:119], v[132:135], v[172:175], v[116:119]
	v_mfma_f32_16x16x32_bf16 v[112:115], v[152:155], v[168:171], v[112:115]
	v_mfma_f32_16x16x32_bf16 v[112:115], v[156:159], v[172:175], v[112:115]
	v_mfma_f32_16x16x32_bf16 v[92:95], v[128:131], v[176:179], v[92:95]
	v_mfma_f32_16x16x32_bf16 v[92:95], v[132:135], v[180:183], v[92:95]
	v_mfma_f32_16x16x32_bf16 v[84:87], v[152:155], v[176:179], v[84:87]
	v_mfma_f32_16x16x32_bf16 v[84:87], v[156:159], v[180:183], v[84:87]
	v_mfma_f32_16x16x32_bf16 v[68:71], v[128:131], v[184:187], v[68:71]
	v_mfma_f32_16x16x32_bf16 v[68:71], v[132:135], v[200:203], v[68:71]
	v_mfma_f32_16x16x32_bf16 v[64:67], v[152:155], v[184:187], v[64:67]
	v_mfma_f32_16x16x32_bf16 v[64:67], v[156:159], v[200:203], v[64:67]
	s_setprio 0
	s_barrier
	s_add_i32 s36, s38, s75
	s_mov_b32 m0, s36
	ds_read_b128 v[160:163], v240 offset:16384
	ds_read_b128 v[164:167], v240 offset:17408
	ds_read_b128 v[168:171], v240 offset:18432
	ds_read_b128 v[172:175], v240 offset:19456
	ds_read_b128 v[176:179], v240 offset:20480
	ds_read_b128 v[180:183], v240 offset:21504
	ds_read_b128 v[184:187], v240 offset:22528
	ds_read_b128 v[200:203], v240 offset:23552
	global_load_lds_dwordx4 v188, s[70:71]
	s_add_i32 m0, s36, 0x2000
	s_add_u32 s36, s70, 0x80000
	s_addc_u32 s37, s71, 0
	s_add_i32 s38, s39, s75
	global_load_lds_dwordx4 v194, s[70:71]
	s_mov_b32 m0, s38
	s_nop 0
	global_load_lds_dwordx4 v188, s[36:37]
	s_add_i32 m0, s38, 0x2000
	s_nop 0
	global_load_lds_dwordx4 v194, s[36:37]
	s_mov_b32 m0, s67
	s_nop 0
	global_load_lds_dwordx4 v188, s[72:73]
	s_mov_b32 m0, s76
	s_nop 0
	global_load_lds_dwordx4 v194, s[72:73]
	s_cmp_eq_u32 s89, -2
	s_cbranch_scc1 .Lew_first_205_1
	s_waitcnt vmcnt(8)
.Lew_join_205_1:
	s_waitcnt lgkmcnt(0)
	s_barrier
	s_setprio 1
	s_waitcnt lgkmcnt(0)
	v_mfma_f32_16x16x32_bf16 v[60:63], v[80:83], v[160:163], v[60:63]
	v_mfma_f32_16x16x32_bf16 v[60:63], v[88:91], v[164:167], v[60:63]
	v_mfma_f32_16x16x32_bf16 v[56:59], v[104:107], v[160:163], v[56:59]
	v_mfma_f32_16x16x32_bf16 v[56:59], v[108:111], v[164:167], v[56:59]
	v_mfma_f32_16x16x32_bf16 v[44:47], v[80:83], v[168:171], v[44:47]
	v_mfma_f32_16x16x32_bf16 v[44:47], v[88:91], v[172:175], v[44:47]
	v_mfma_f32_16x16x32_bf16 v[40:43], v[104:107], v[168:171], v[40:43]
	v_mfma_f32_16x16x32_bf16 v[40:43], v[108:111], v[172:175], v[40:43]
	v_mfma_f32_16x16x32_bf16 v[28:31], v[80:83], v[176:179], v[28:31]
	v_mfma_f32_16x16x32_bf16 v[28:31], v[88:91], v[180:183], v[28:31]
	v_mfma_f32_16x16x32_bf16 v[24:27], v[104:107], v[176:179], v[24:27]
	v_mfma_f32_16x16x32_bf16 v[24:27], v[108:111], v[180:183], v[24:27]
	v_mfma_f32_16x16x32_bf16 v[12:15], v[80:83], v[184:187], v[12:15]
	v_mfma_f32_16x16x32_bf16 v[12:15], v[88:91], v[200:203], v[12:15]
	v_mfma_f32_16x16x32_bf16 v[8:11], v[104:107], v[184:187], v[8:11]
	v_mfma_f32_16x16x32_bf16 v[8:11], v[108:111], v[200:203], v[8:11]
	s_setprio 0
	s_setprio 1
	v_mfma_f32_16x16x32_bf16 v[52:55], v[128:131], v[160:163], v[52:55]
	v_mfma_f32_16x16x32_bf16 v[52:55], v[132:135], v[164:167], v[52:55]
	v_mfma_f32_16x16x32_bf16 v[48:51], v[152:155], v[160:163], v[48:51]
	v_mfma_f32_16x16x32_bf16 v[48:51], v[156:159], v[164:167], v[48:51]
	v_mfma_f32_16x16x32_bf16 v[36:39], v[128:131], v[168:171], v[36:39]
	v_mfma_f32_16x16x32_bf16 v[36:39], v[132:135], v[172:175], v[36:39]
	v_mfma_f32_16x16x32_bf16 v[32:35], v[152:155], v[168:171], v[32:35]
	v_mfma_f32_16x16x32_bf16 v[32:35], v[156:159], v[172:175], v[32:35]
	v_mfma_f32_16x16x32_bf16 v[20:23], v[128:131], v[176:179], v[20:23]
	v_mfma_f32_16x16x32_bf16 v[20:23], v[132:135], v[180:183], v[20:23]
	v_mfma_f32_16x16x32_bf16 v[16:19], v[152:155], v[176:179], v[16:19]
	v_mfma_f32_16x16x32_bf16 v[16:19], v[156:159], v[180:183], v[16:19]
	v_mfma_f32_16x16x32_bf16 v[4:7], v[128:131], v[184:187], v[4:7]
	v_mfma_f32_16x16x32_bf16 v[4:7], v[132:135], v[200:203], v[4:7]
	v_mfma_f32_16x16x32_bf16 v[0:3], v[152:155], v[184:187], v[0:3]
	v_mfma_f32_16x16x32_bf16 v[0:3], v[156:159], v[200:203], v[0:3]
	s_setprio 0
	s_barrier
; #define PG8_STAGE(bufoff, gbase, voff) do { _Pragma("unroll") for (int _i = 0; _i < 2; ++_i) \
;         __builtin_amdgcn_global_load_lds((const unsigned*)((const char*)(gbase) + (voff)[_i]), (PG8_LAS unsigned*)(lds + (bufoff) + ldsw + _i * 8192), 16, 0, 0); } while (0)
; #define PG8_LDA(dst, b, h) do { _Pragma("unroll") for (int m = 0; m < 4; ++m) _Pragma("unroll") for (int k = 0; k < 2; ++k) dst[m][k] = *(const PG8_LAS bf16x8*)(lds + PG8_SA(b, h) + aoff + m * 2048 + k * 1024); } while (0)
; #define PG8_LDB(dst, b, h) do { _Pragma("unroll") for (int n = 0; n < 2; ++n) _Pragma("unroll") for (int k = 0; k < 2; ++k) dst[n][k] = *(const PG8_LAS bf16x8*)(lds + PG8_SB(b, h) + boff + n * 2048 + k * 1024); } while (0)
; #define PG8_MMA(ai, bj, At, Bt) do { __builtin_amdgcn_s_setprio(1); _Pragma("unroll") for (int m = 0; m < 4; ++m) _Pragma("unroll") for (int n = 0; n < 2; ++n) _Pragma("unroll") for (int k = 0; k < 2; ++k) \
;         acc[ai][bj][m][n] = __builtin_amdgcn_mfma_f32_16x16x32_bf16(Bt[n][k], At[m][k], acc[ai][bj][m][n], 0, 0, 0); __builtin_amdgcn_s_setprio(0); } while (0)
; #define PG8_WAIT_V(n) asm volatile("s_waitcnt vmcnt(" #n ")" ::: "memory")
; #define PG8_WAIT_L(n) asm volatile("s_waitcnt lgkmcnt(" #n ")" ::: "memory")
; #define PG8_BAR __builtin_amdgcn_s_barrier()
; #define PG8_SCHED __builtin_amdgcn_sched_barrier(0)
; template <class Epi, class Sched, bool ALIGN_EPI = false, bool SP2 = false>
; __device__ __forceinline__ void gemm_phase(PG8_LAS unsigned char* lds, const Gemm g, const Sched& S, const Epi& E) {
;     ...
;         for (int t = 0; t < nt; t += 2) {
;     ...
;             PG8_LDB(B0, 1, 0); PG8_LDB(B1, 1, 1); PG8_SCHED; PG8_LDA(At, 1, 0); PG8_STAGE(PG8_SA(0, 1), a2 + hstep, voffA);
;             PG8_WAIT_V(8); PG8_WAIT_L(0); PG8_BAR; PG8_MMA(0, 0, At, B0); PG8_MMA(0, 1, At, B1); PG8_BAR; PG8_SCHED;
;             PG8_LDA(At, 1, 1); PG8_STAGE(PG8_SB(1, 0), b3, voffB); PG8_STAGE(PG8_SB(1, 1), b3 + hstep, voffB); PG8_STAGE(PG8_SA(1, 0), a3, voffA);
;             PG8_WAIT_V(8); PG8_WAIT_L(0); PG8_BAR; PG8_MMA(1, 0, At, B0); PG8_MMA(1, 1, At, B1); PG8_BAR; PG8_SCHED;
	s_add_i32 s38, 0, 0x18000
	s_add_i32 s39, 0, 0x1c000
	ds_read_b128 v[80:83], v204 offset:32768
	ds_read_b128 v[88:91], v204 offset:33792
	ds_read_b128 v[104:107], v204 offset:34816
	ds_read_b128 v[108:111], v204 offset:35840
	ds_read_b128 v[128:131], v204 offset:49152
	ds_read_b128 v[132:135], v204 offset:50176
	ds_read_b128 v[152:155], v204 offset:51200
	ds_read_b128 v[156:159], v204 offset:52224
	s_add_u32 s36, s72, 0x80000
	s_addc_u32 s37, s73, 0
	s_mov_b32 m0, s77
	ds_read_b128 v[160:163], v240 offset:32768
	ds_read_b128 v[164:167], v240 offset:33792
	ds_read_b128 v[168:171], v240 offset:34816
	ds_read_b128 v[172:175], v240 offset:35840
	ds_read_b128 v[176:179], v240 offset:36864
	ds_read_b128 v[180:183], v240 offset:37888
	ds_read_b128 v[184:187], v240 offset:38912
	ds_read_b128 v[200:203], v240 offset:39936
	global_load_lds_dwordx4 v188, s[36:37]
	s_mov_b32 m0, s78
	s_nop 0
	global_load_lds_dwordx4 v194, s[36:37]
	s_waitcnt vmcnt(8)
	s_waitcnt lgkmcnt(0)
	s_barrier
	s_setprio 1
	s_waitcnt lgkmcnt(0)
	v_mfma_f32_16x16x32_bf16 v[148:151], v[80:83], v[160:163], v[148:151]
	v_mfma_f32_16x16x32_bf16 v[148:151], v[88:91], v[164:167], v[148:151]
	v_mfma_f32_16x16x32_bf16 v[144:147], v[104:107], v[160:163], v[144:147]
	v_mfma_f32_16x16x32_bf16 v[144:147], v[108:111], v[164:167], v[144:147]
	v_mfma_f32_16x16x32_bf16 v[124:127], v[80:83], v[168:171], v[124:127]
	v_mfma_f32_16x16x32_bf16 v[124:127], v[88:91], v[172:175], v[124:127]
	v_mfma_f32_16x16x32_bf16 v[120:123], v[104:107], v[168:171], v[120:123]
	v_mfma_f32_16x16x32_bf16 v[120:123], v[108:111], v[172:175], v[120:123]
	v_mfma_f32_16x16x32_bf16 v[100:103], v[80:83], v[176:179], v[100:103]
	v_mfma_f32_16x16x32_bf16 v[100:103], v[88:91], v[180:183], v[100:103]
	v_mfma_f32_16x16x32_bf16 v[96:99], v[104:107], v[176:179], v[96:99]
	v_mfma_f32_16x16x32_bf16 v[96:99], v[108:111], v[180:183], v[96:99]
	v_mfma_f32_16x16x32_bf16 v[76:79], v[80:83], v[184:187], v[76:79]
	v_mfma_f32_16x16x32_bf16 v[76:79], v[88:91], v[200:203], v[76:79]
	v_mfma_f32_16x16x32_bf16 v[72:75], v[104:107], v[184:187], v[72:75]
	v_mfma_f32_16x16x32_bf16 v[72:75], v[108:111], v[200:203], v[72:75]
	s_setprio 0
	s_setprio 1
	v_mfma_f32_16x16x32_bf16 v[140:143], v[128:131], v[160:163], v[140:143]
	v_mfma_f32_16x16x32_bf16 v[140:143], v[132:135], v[164:167], v[140:143]
	v_mfma_f32_16x16x32_bf16 v[136:139], v[152:155], v[160:163], v[136:139]
	v_mfma_f32_16x16x32_bf16 v[136:139], v[156:159], v[164:167], v[136:139]
	v_mfma_f32_16x16x32_bf16 v[116:119], v[128:131], v[168:171], v[116:119]
	v_mfma_f32_16x16x32_bf16 v[116:119], v[132:135], v[172:175], v[116:119]
	v_mfma_f32_16x16x32_bf16 v[112:115], v[152:155], v[168:171], v[112:115]
	v_mfma_f32_16x16x32_bf16 v[112:115], v[156:159], v[172:175], v[112:115]
	v_mfma_f32_16x16x32_bf16 v[92:95], v[128:131], v[176:179], v[92:95]
	v_mfma_f32_16x16x32_bf16 v[92:95], v[132:135], v[180:183], v[92:95]
	v_mfma_f32_16x16x32_bf16 v[84:87], v[152:155], v[176:179], v[84:87]
	v_mfma_f32_16x16x32_bf16 v[84:87], v[156:159], v[180:183], v[84:87]
	v_mfma_f32_16x16x32_bf16 v[68:71], v[128:131], v[184:187], v[68:71]
	v_mfma_f32_16x16x32_bf16 v[68:71], v[132:135], v[200:203], v[68:71]
	v_mfma_f32_16x16x32_bf16 v[64:67], v[152:155], v[184:187], v[64:67]
	v_mfma_f32_16x16x32_bf16 v[64:67], v[156:159], v[200:203], v[64:67]
	s_setprio 0
	s_barrier
	s_add_i32 s36, s38, s75
	s_mov_b32 m0, s36
	ds_read_b128 v[160:163], v240 offset:49152
	ds_read_b128 v[164:167], v240 offset:50176
	ds_read_b128 v[168:171], v240 offset:51200
	ds_read_b128 v[172:175], v240 offset:52224
	ds_read_b128 v[176:179], v240 offset:53248
	ds_read_b128 v[180:183], v240 offset:54272
	ds_read_b128 v[184:187], v240 offset:55296
	ds_read_b128 v[200:203], v240 offset:56320
	s_add_u32 s100, s70, 0x80
	s_addc_u32 s101, s71, 0
	global_load_lds_dwordx4 v188, s[100:101]
	s_add_i32 m0, s36, 0x2000
	s_add_u32 s36, s70, 0x80080
	s_addc_u32 s37, s71, 0
	s_add_i32 s38, s39, s75
	global_load_lds_dwordx4 v194, s[100:101]
	s_mov_b32 m0, s38
	s_nop 0
	global_load_lds_dwordx4 v188, s[36:37]
	s_add_i32 m0, s38, 0x2000
	s_nop 0
	global_load_lds_dwordx4 v194, s[36:37]
	s_mov_b32 m0, s79
	s_nop 0
	s_add_u32 s100, s72, 0x80
	s_addc_u32 s101, s73, 0
	global_load_lds_dwordx4 v188, s[100:101]
	s_mov_b32 m0, s80
	s_nop 0
	global_load_lds_dwordx4 v194, s[100:101]
	s_waitcnt vmcnt(8)
	s_waitcnt lgkmcnt(0)
	s_barrier
	s_setprio 1
	s_waitcnt lgkmcnt(0)
	v_mfma_f32_16x16x32_bf16 v[60:63], v[80:83], v[160:163], v[60:63]
	v_mfma_f32_16x16x32_bf16 v[60:63], v[88:91], v[164:167], v[60:63]
	v_mfma_f32_16x16x32_bf16 v[56:59], v[104:107], v[160:163], v[56:59]
	v_mfma_f32_16x16x32_bf16 v[56:59], v[108:111], v[164:167], v[56:59]
	v_mfma_f32_16x16x32_bf16 v[44:47], v[80:83], v[168:171], v[44:47]
	v_mfma_f32_16x16x32_bf16 v[44:47], v[88:91], v[172:175], v[44:47]
	v_mfma_f32_16x16x32_bf16 v[40:43], v[104:107], v[168:171], v[40:43]
	v_mfma_f32_16x16x32_bf16 v[40:43], v[108:111], v[172:175], v[40:43]
	v_mfma_f32_16x16x32_bf16 v[28:31], v[80:83], v[176:179], v[28:31]
	v_mfma_f32_16x16x32_bf16 v[28:31], v[88:91], v[180:183], v[28:31]
	v_mfma_f32_16x16x32_bf16 v[24:27], v[104:107], v[176:179], v[24:27]
	v_mfma_f32_16x16x32_bf16 v[24:27], v[108:111], v[180:183], v[24:27]
	v_mfma_f32_16x16x32_bf16 v[12:15], v[80:83], v[184:187], v[12:15]
	v_mfma_f32_16x16x32_bf16 v[12:15], v[88:91], v[200:203], v[12:15]
	v_mfma_f32_16x16x32_bf16 v[8:11], v[104:107], v[184:187], v[8:11]
	v_mfma_f32_16x16x32_bf16 v[8:11], v[108:111], v[200:203], v[8:11]
	s_setprio 0
	s_setprio 1
	v_mfma_f32_16x16x32_bf16 v[52:55], v[128:131], v[160:163], v[52:55]
	v_mfma_f32_16x16x32_bf16 v[52:55], v[132:135], v[164:167], v[52:55]
	v_mfma_f32_16x16x32_bf16 v[48:51], v[152:155], v[160:163], v[48:51]
	v_mfma_f32_16x16x32_bf16 v[48:51], v[156:159], v[164:167], v[48:51]
	v_mfma_f32_16x16x32_bf16 v[36:39], v[128:131], v[168:171], v[36:39]
	v_mfma_f32_16x16x32_bf16 v[36:39], v[132:135], v[172:175], v[36:39]
	v_mfma_f32_16x16x32_bf16 v[32:35], v[152:155], v[168:171], v[32:35]
	v_mfma_f32_16x16x32_bf16 v[32:35], v[156:159], v[172:175], v[32:35]
	v_mfma_f32_16x16x32_bf16 v[20:23], v[128:131], v[176:179], v[20:23]
	v_mfma_f32_16x16x32_bf16 v[20:23], v[132:135], v[180:183], v[20:23]
	v_mfma_f32_16x16x32_bf16 v[16:19], v[152:155], v[176:179], v[16:19]
	v_mfma_f32_16x16x32_bf16 v[16:19], v[156:159], v[180:183], v[16:19]
	v_mfma_f32_16x16x32_bf16 v[4:7], v[128:131], v[184:187], v[4:7]
	v_mfma_f32_16x16x32_bf16 v[4:7], v[132:135], v[200:203], v[4:7]
	v_mfma_f32_16x16x32_bf16 v[0:3], v[152:155], v[184:187], v[0:3]
	v_mfma_f32_16x16x32_bf16 v[0:3], v[156:159], v[200:203], v[0:3]
	s_setprio 0
	s_barrier
	s_add_i32 s89, s89, 2
	s_add_u32 s68, s68, 0x100
	s_addc_u32 s69, s69, 0
	s_add_u32 s3, s3, 0x100
	s_addc_u32 s88, s88, 0
	s_cmp_gt_u32 s89, 29
	s_cbranch_scc0 .LBB0_205
	s_and_b64 vcc, exec, s[56:57]
	s_cbranch_vccz .LBB0_208
	s_barrier

; #define PG8_STAGE(bufoff, gbase, voff) do { _Pragma("unroll") for (int _i = 0; _i < 2; ++_i) \
;         __builtin_amdgcn_global_load_lds((const unsigned*)((const char*)(gbase) + (voff)[_i]), (PG8_LAS unsigned*)(lds + (bufoff) + ldsw + _i * 8192), 16, 0, 0); } while (0)
; #define PG8_LDA(dst, b, h) do { _Pragma("unroll") for (int m = 0; m < 4; ++m) _Pragma("unroll") for (int k = 0; k < 2; ++k) dst[m][k] = *(const PG8_LAS bf16x8*)(lds + PG8_SA(b, h) + aoff + m * 2048 + k * 1024); } while (0)
; #define PG8_MMA(ai, bj, At, Bt) do { __builtin_amdgcn_s_setprio(1); _Pragma("unroll") for (int m = 0; m < 4; ++m) _Pragma("unroll") for (int n = 0; n < 2; ++n) _Pragma("unroll") for (int k = 0; k < 2; ++k) \
;         acc[ai][bj][m][n] = __builtin_amdgcn_mfma_f32_16x16x32_bf16(Bt[n][k], At[m][k], acc[ai][bj][m][n], 0, 0, 0); __builtin_amdgcn_s_setprio(0); } while (0)
; #define PG8_WAIT_V(n) asm volatile("s_waitcnt vmcnt(" #n ")" ::: "memory")
; #define PG8_WAIT_L(n) asm volatile("s_waitcnt lgkmcnt(" #n ")" ::: "memory")
; #define PG8_BAR __builtin_amdgcn_s_barrier()
; #define PG8_SCHED __builtin_amdgcn_sched_barrier(0)
; template <class Epi, class Sched, bool ALIGN_EPI = false, bool SP2 = false>
; __device__ __forceinline__ void gemm_phase(PG8_LAS unsigned char* lds, const Gemm g, const Sched& S, const Epi& E) {
;     ...
;             PG8_WAIT_V(8); PG8_WAIT_L(0); PG8_BAR; PG8_MMA(0, 0, At, B0); PG8_MMA(0, 1, At, B1); PG8_BAR; PG8_SCHED;
;             PG8_LDA(At, 0, 1); PG8_STAGE(PG8_SB(0, 0), b2, voffB); PG8_STAGE(PG8_SB(0, 1), b2 + hstep, voffB); PG8_STAGE(PG8_SA(0, 0), a2, voffA);
;             PG8_WAIT_V(8); PG8_WAIT_L(0); PG8_BAR; PG8_MMA(1, 0, At, B0); PG8_MMA(1, 1, At, B1); PG8_BAR; PG8_SCHED;
.Lew_first_205_1:
	s_waitcnt vmcnt(24)
	s_branch .Lew_join_205_1

; #define PG8_STAGE(bufoff, gbase, voff) do { _Pragma("unroll") for (int _i = 0; _i < 2; ++_i) \
;         __builtin_amdgcn_global_load_lds((const unsigned*)((const char*)(gbase) + (voff)[_i]), (PG8_LAS unsigned*)(lds + (bufoff) + ldsw + _i * 8192), 16, 0, 0); } while (0)
; #define PG8_WAIT_V(n) asm volatile("s_waitcnt vmcnt(" #n ")" ::: "memory")
; #define PG8_BAR __builtin_amdgcn_s_barrier()
; template <class Epi, class Sched, bool ALIGN_EPI = false, bool SP2 = false>
; __device__ __forceinline__ void gemm_phase(PG8_LAS unsigned char* lds, const Gemm g, const Sched& S, const Epi& E) {
;     ...
;         PG8_STAGE(PG8_SB(0, 0), cB, voffB); PG8_STAGE(PG8_SB(0, 1), cB + hstep, voffB); PG8_STAGE(PG8_SA(0, 0), cA, voffA); PG8_STAGE(PG8_SA(0, 1), cA + hstep, voffA);
;         if (wr == 1) PG8_BAR;
;         PG8_WAIT_V(2); PG8_BAR;
;         PG8_STAGE(PG8_SB(1, 0), cB + kstep, voffB); PG8_STAGE(PG8_SA(1, 0), cA + kstep, voffA); PG8_STAGE(PG8_SB(1, 1), cB + hstep + kstep, voffB);
;         PG8_WAIT_V(6); PG8_BAR;
.LBB0_292:
	v_bfe_u32 v16, v8, 4, 2
	s_mov_b32 s8, s44
	v_and_b32_e32 v15, 15, v8
	v_lshlrev_b32_e32 v17, 4, v16
	v_lshlrev_b32_e32 v19, 2, v8
	v_writelane_b32 v255, s8, 16
	s_and_b32 s6, s4, 3
	v_lshl_or_b32 v18, v15, 6, v17
	s_lshl_b32 s4, s5, 13
	v_and_b32_e32 v19, 32, v19
	v_writelane_b32 v255, s9, 17
	v_lshl_or_b32 v164, s5, 6, v15
	v_bitop3_b32 v20, v18, s4, v19 bitop3:0xde
	s_lshl_b32 s4, s6, 12
	s_mul_i32 s5, s44, 0x6000
	v_readlane_b32 s36, v255, 6
	v_bitop3_b32 v165, v18, s4, v19 bitop3:0xde
	s_mul_hi_i32 s4, s44, 0x6000
	v_readlane_b32 s37, v255, 7
	s_add_u32 s56, s36, s5
	s_addc_u32 s57, s37, s4
	s_add_i32 m0, s88, 0x18000
	v_lshl_add_u64 v[6:7], v[6:7], 0, s[90:91]
	s_waitcnt vmcnt(2)
	s_barrier
	global_load_lds_dwordx4 v[6:7], off
	v_lshl_add_u64 v[4:5], v[4:5], 0, s[90:91]
	s_add_i32 m0, s88, 0x1a000
	s_add_i32 s81, s88, 0x8000
	s_add_i32 s80, s88, 0xa000
	global_load_lds_dwordx4 v[4:5], off
	v_lshl_add_u64 v[0:1], v[0:1], 0, s[90:91]
	s_mov_b32 m0, s81
	s_add_u32 s4, s70, 0x80080
	global_load_lds_dwordx4 v[0:1], off
	v_lshl_add_u64 v[0:1], v[2:3], 0, s[90:91]
	s_mov_b32 m0, s80
	s_addc_u32 s5, s71, 0
	global_load_lds_dwordx4 v[0:1], off
	s_add_i32 m0, s88, 0x1c000
	v_lshl_add_u64 v[0:1], s[4:5], 0, v[188:189]
	global_load_lds_dwordx4 v[0:1], off
	v_lshl_add_u64 v[0:1], s[4:5], 0, v[140:141]
	s_add_i32 m0, s88, 0x1e000
	s_cmpk_lt_u32 s3, 0x100
	global_load_lds_dwordx4 v[0:1], off
	v_lshlrev_b32_e32 v0, 2, v16
	v_lshl_or_b32 v166, s6, 4, v0
	v_add_u32_e32 v0, -1, v8
	v_and_or_b32 v167, v0, 15, v17
	v_add_u32_e32 v0, 1, v8
	v_and_or_b32 v168, v0, 15, v17
	v_lshlrev_b32_e32 v0, 15, v9
	v_and_b32_e32 v0, 0xffff0000, v0
	v_lshl_add_u32 v0, v10, 12, v0
	v_and_b32_e32 v1, 1, v9
	v_lshl_or_b32 v0, v1, 6, v0
	s_cselect_b64 s[58:59], -1, 0
	s_waitcnt lgkmcnt(0)
	s_ashr_i32 s55, s86, 31
	s_lshl_b32 s44, s45, 2
	v_lshl_add_u32 v142, v11, 1, v0
	v_lshlrev_b32_e32 v0, 15, v12
	s_add_u32 s60, s56, 0x2000
	v_and_b32_e32 v0, 0xffff0000, v0
	s_waitcnt vmcnt(0)
	s_addc_u32 s61, s57, 0
	v_lshl_add_u32 v0, v13, 12, v0
	v_and_b32_e32 v1, 1, v12
	s_add_u32 s62, s56, 0x4000
	v_lshl_or_b32 v0, v1, 6, v0
	s_mov_b32 s54, 0
	v_cmp_eq_u32_e64 s[4:5], 0, v15
	v_cmp_eq_u32_e64 s[6:7], 15, v15
	v_cmp_gt_u32_e64 s[8:9], 2, v15
	v_cmp_lt_u32_e64 s[10:11], 13, v15
	s_addc_u32 s63, s57, 0
	v_mov_b32_e32 v143, v189
	v_lshl_add_u32 v144, v14, 1, v0
	v_mov_b32_e32 v145, v189
	v_add_u32_e32 v169, 0, v20
	v_readlane_b32 s38, v255, 8
	v_readlane_b32 s39, v255, 9
	v_readlane_b32 s40, v255, 10
	v_readlane_b32 s41, v255, 11
	v_readlane_b32 s42, v255, 12
	v_readlane_b32 s43, v255, 13
	s_barrier
	s_branch .LBB0_295

; #define PG8_STAGE(bufoff, gbase, voff) do { _Pragma("unroll") for (int _i = 0; _i < 2; ++_i) \
;         __builtin_amdgcn_global_load_lds((const unsigned*)((const char*)(gbase) + (voff)[_i]), (PG8_LAS unsigned*)(lds + (bufoff) + ldsw + _i * 8192), 16, 0, 0); } while (0)
; #define PG8_LDA(dst, b, h) do { _Pragma("unroll") for (int m = 0; m < 4; ++m) _Pragma("unroll") for (int k = 0; k < 2; ++k) dst[m][k] = *(const PG8_LAS bf16x8*)(lds + PG8_SA(b, h) + aoff + m * 2048 + k * 1024); } while (0)
; #define PG8_LDB(dst, b, h) do { _Pragma("unroll") for (int n = 0; n < 2; ++n) _Pragma("unroll") for (int k = 0; k < 2; ++k) dst[n][k] = *(const PG8_LAS bf16x8*)(lds + PG8_SB(b, h) + boff + n * 2048 + k * 1024); } while (0)
; #define PG8_SCHED __builtin_amdgcn_sched_barrier(0)
; template <class Epi, class Sched, bool ALIGN_EPI = false, bool SP2 = false>
; __device__ __forceinline__ void gemm_phase(PG8_LAS unsigned char* lds, const Gemm g, const Sched& S, const Epi& E) {
;     ...
;         for (int t = 0; t < nt; t += 2) {
;             const bool last = (t == nt - 2);
;             const char* a1 = cA + (size_t)(t + 1) * kstep;
;             const char* a2 = last ? nA : cA + (size_t)(t + 2) * kstep; const char* b2 = last ? nB : cB + (size_t)(t + 2) * kstep;
;             const char* a3 = a2 + kstep; const char* b3 = b2 + kstep;
;             if (last && has_next) S.a_ready(nxt);
;             if constexpr (SP2) {
;             PG8_LDB(B0, 0, 0); PG8_LDB(B1, 0, 1); PG8_SCHED; PG8_LDA(At, 0, 0); PG8_STAGE(PG8_SA(1, 1), a1 + hstep, voffA);
;     ...
;         for (int a = 0; a < 2; ++a)
; #pragma unroll
;             for (int b = 0; b < 2; ++b)
; #pragma unroll
;                 for (int m = 0; m < 4; ++m)
; #pragma unroll
;                     for (int n = 0; n < 2; ++n) acc[a][b][m][n] = (f32x4){0.f, 0.f, 0.f, 0.f};
;         cur = nxt; cA = nA; cB = nB; ++ui;
.LBB0_297:
	s_ashr_i32 s67, s66, 31
	s_lshl_b64 s[76:77], s[66:67], 20
	s_add_u32 s78, s34, s76
	s_addc_u32 s79, s35, s77
	s_and_b64 s[76:77], s[12:13], exec
	s_cselect_b32 s65, s79, s69
	s_cselect_b32 s67, s78, s68
	s_ashr_i32 s75, s74, 31
	s_lshl_b64 s[76:77], s[74:75], 20
	s_add_u32 s76, s0, s76
	s_addc_u32 s77, s1, s77
	s_and_b64 s[94:95], s[12:13], exec
	s_cselect_b32 s73, s77, s71
	s_cselect_b32 s75, s76, s70
	s_add_u32 vcc_lo, s68, 0x80080
	s_addc_u32 vcc_hi, s69, 0
	s_add_u32 s3, s70, 0x100
	v_mov_b32_e32 v0, 0
	s_addc_u32 s94, s71, 0
	s_mov_b32 s95, -2
	v_mov_b32_e32 v1, v0
	v_mov_b32_e32 v2, v0
	v_mov_b32_e32 v3, v0
	v_mov_b32_e32 v4, v0
	v_mov_b32_e32 v5, v0
	v_mov_b32_e32 v6, v0
	v_mov_b32_e32 v7, v0
	v_mov_b32_e32 v16, v0
	v_mov_b32_e32 v17, v0
	v_mov_b32_e32 v18, v0
	v_mov_b32_e32 v19, v0
	v_mov_b32_e32 v20, v0
	v_mov_b32_e32 v21, v0
	v_mov_b32_e32 v22, v0
	v_mov_b32_e32 v23, v0
	v_mov_b32_e32 v32, v0
	v_mov_b32_e32 v33, v0
	v_mov_b32_e32 v34, v0
	v_mov_b32_e32 v35, v0
	v_mov_b32_e32 v36, v0
	v_mov_b32_e32 v37, v0
	v_mov_b32_e32 v38, v0
	v_mov_b32_e32 v39, v0
	v_mov_b32_e32 v48, v0
	v_mov_b32_e32 v49, v0
	v_mov_b32_e32 v50, v0
	v_mov_b32_e32 v51, v0
	v_mov_b32_e32 v52, v0
	v_mov_b32_e32 v53, v0
	v_mov_b32_e32 v54, v0
	v_mov_b32_e32 v55, v0
	v_mov_b32_e32 v12, v0
	v_mov_b32_e32 v13, v0
	v_mov_b32_e32 v14, v0
	v_mov_b32_e32 v15, v0
	v_mov_b32_e32 v8, v0
	v_mov_b32_e32 v9, v0
	v_mov_b32_e32 v10, v0
	v_mov_b32_e32 v11, v0
	v_mov_b32_e32 v28, v0
	v_mov_b32_e32 v29, v0
	v_mov_b32_e32 v30, v0
	v_mov_b32_e32 v31, v0
	v_mov_b32_e32 v24, v0
	v_mov_b32_e32 v25, v0
	v_mov_b32_e32 v26, v0
	v_mov_b32_e32 v27, v0
	v_mov_b32_e32 v44, v0
	v_mov_b32_e32 v45, v0
	v_mov_b32_e32 v46, v0
	v_mov_b32_e32 v47, v0
	v_mov_b32_e32 v40, v0
	v_mov_b32_e32 v41, v0
	v_mov_b32_e32 v42, v0
	v_mov_b32_e32 v43, v0
	v_mov_b32_e32 v60, v0
	v_mov_b32_e32 v61, v0
	v_mov_b32_e32 v62, v0
	v_mov_b32_e32 v63, v0
	v_mov_b32_e32 v56, v0
	v_mov_b32_e32 v57, v0
	v_mov_b32_e32 v58, v0
	v_mov_b32_e32 v59, v0
	v_mov_b32_e32 v76, v0
	v_mov_b32_e32 v77, v0
	v_mov_b32_e32 v78, v0
	v_mov_b32_e32 v79, v0
	v_mov_b32_e32 v80, v0
	v_mov_b32_e32 v81, v0
	v_mov_b32_e32 v82, v0
	v_mov_b32_e32 v83, v0
	v_mov_b32_e32 v92, v0
	v_mov_b32_e32 v93, v0
	v_mov_b32_e32 v94, v0
	v_mov_b32_e32 v95, v0
	v_mov_b32_e32 v96, v0
	v_mov_b32_e32 v97, v0
	v_mov_b32_e32 v98, v0
	v_mov_b32_e32 v99, v0
	v_mov_b32_e32 v108, v0
	v_mov_b32_e32 v109, v0
	v_mov_b32_e32 v110, v0
	v_mov_b32_e32 v111, v0
	v_mov_b32_e32 v112, v0
	v_mov_b32_e32 v113, v0
	v_mov_b32_e32 v114, v0
	v_mov_b32_e32 v115, v0
	v_mov_b32_e32 v124, v0
	v_mov_b32_e32 v125, v0
	v_mov_b32_e32 v126, v0
	v_mov_b32_e32 v127, v0
	v_mov_b32_e32 v128, v0
	v_mov_b32_e32 v129, v0
	v_mov_b32_e32 v130, v0
	v_mov_b32_e32 v131, v0
	v_mov_b32_e32 v84, v0
	v_mov_b32_e32 v85, v0
	v_mov_b32_e32 v86, v0
	v_mov_b32_e32 v87, v0
	v_mov_b32_e32 v88, v0
	v_mov_b32_e32 v89, v0
	v_mov_b32_e32 v90, v0
	v_mov_b32_e32 v91, v0
	v_mov_b32_e32 v100, v0
	v_mov_b32_e32 v101, v0
	v_mov_b32_e32 v102, v0
	v_mov_b32_e32 v103, v0
	v_mov_b32_e32 v104, v0
	v_mov_b32_e32 v105, v0
	v_mov_b32_e32 v106, v0
	v_mov_b32_e32 v107, v0
	v_mov_b32_e32 v116, v0
	v_mov_b32_e32 v117, v0
	v_mov_b32_e32 v118, v0
	v_mov_b32_e32 v119, v0
	v_mov_b32_e32 v120, v0
	v_mov_b32_e32 v121, v0
	v_mov_b32_e32 v122, v0
	v_mov_b32_e32 v123, v0
	v_mov_b32_e32 v132, v0
	v_mov_b32_e32 v133, v0
	v_mov_b32_e32 v134, v0
	v_mov_b32_e32 v135, v0
	v_mov_b32_e32 v136, v0
	v_mov_b32_e32 v137, v0
	v_mov_b32_e32 v138, v0
	v_mov_b32_e32 v139, v0
	s_waitcnt vmcnt(8)
	v_add_u32_e32 v214, 0x10000, v165
.LBB0_298:
	s_add_u32 s36, vcc_lo, 0xfff80080
	s_addc_u32 s37, vcc_hi, -1
	s_add_i32 s38, 0, 0x10000
	s_cmp_eq_u32 s95, 28
	s_cselect_b32 s71, s65, s37
	s_cselect_b32 s70, s67, s36
	s_cselect_b32 s69, s73, s94
	s_cselect_b32 s68, s75, s3
	s_add_i32 s39, 0, 0x14000
	ds_read_b128 v[64:67], v214
	ds_read_b128 v[68:71], v214 offset:1024
	ds_read_b128 v[72:75], v214 offset:2048
	ds_read_b128 v[146:149], v214 offset:3072
	ds_read_b128 v[150:153], v214 offset:16384
	ds_read_b128 v[154:157], v214 offset:17408
	ds_read_b128 v[158:161], v214 offset:18432
	ds_read_b128 v[170:173], v214 offset:19456
	s_add_i32 m0, s88, 0xc000
	ds_read_b128 v[174:177], v169
	ds_read_b128 v[178:181], v169 offset:1024
	ds_read_b128 v[182:185], v169 offset:2048
	ds_read_b128 v[194:197], v169 offset:3072
	ds_read_b128 v[198:201], v169 offset:4096
	ds_read_b128 v[202:205], v169 offset:5120
	ds_read_b128 v[206:209], v169 offset:6144
	ds_read_b128 v[210:213], v169 offset:7168
	global_load_lds_dwordx4 v142, vcc
	s_add_i32 m0, s88, 0xe000
	s_nop 0
	global_load_lds_dwordx4 v144, vcc
	s_cmp_eq_u32 s95, -2
	s_cbranch_scc1 .Lew_first_298_0
	s_waitcnt vmcnt(8)
; #define PG8_STAGE(bufoff, gbase, voff) do { _Pragma("unroll") for (int _i = 0; _i < 2; ++_i) \
;         __builtin_amdgcn_global_load_lds((const unsigned*)((const char*)(gbase) + (voff)[_i]), (PG8_LAS unsigned*)(lds + (bufoff) + ldsw + _i * 8192), 16, 0, 0); } while (0)
; #define PG8_LDA(dst, b, h) do { _Pragma("unroll") for (int m = 0; m < 4; ++m) _Pragma("unroll") for (int k = 0; k < 2; ++k) dst[m][k] = *(const PG8_LAS bf16x8*)(lds + PG8_SA(b, h) + aoff + m * 2048 + k * 1024); } while (0)
; #define PG8_LDB(dst, b, h) do { _Pragma("unroll") for (int n = 0; n < 2; ++n) _Pragma("unroll") for (int k = 0; k < 2; ++k) dst[n][k] = *(const PG8_LAS bf16x8*)(lds + PG8_SB(b, h) + boff + n * 2048 + k * 1024); } while (0)
; #define PG8_MMA(ai, bj, At, Bt) do { __builtin_amdgcn_s_setprio(1); _Pragma("unroll") for (int m = 0; m < 4; ++m) _Pragma("unroll") for (int n = 0; n < 2; ++n) _Pragma("unroll") for (int k = 0; k < 2; ++k) \
;         acc[ai][bj][m][n] = __builtin_amdgcn_mfma_f32_16x16x32_bf16(Bt[n][k], At[m][k], acc[ai][bj][m][n], 0, 0, 0); __builtin_amdgcn_s_setprio(0); } while (0)
; #define PG8_WAIT_V(n) asm volatile("s_waitcnt vmcnt(" #n ")" ::: "memory")
; #define PG8_WAIT_L(n) asm volatile("s_waitcnt lgkmcnt(" #n ")" ::: "memory")
; #define PG8_BAR __builtin_amdgcn_s_barrier()
; #define PG8_SCHED __builtin_amdgcn_sched_barrier(0)
; template <class Epi, class Sched, bool ALIGN_EPI = false, bool SP2 = false>
; __device__ __forceinline__ void gemm_phase(PG8_LAS unsigned char* lds, const Gemm g, const Sched& S, const Epi& E) {
;     ...
;             PG8_LDB(B0, 0, 0); PG8_LDB(B1, 0, 1); PG8_SCHED; PG8_LDA(At, 0, 0); PG8_STAGE(PG8_SA(1, 1), a1 + hstep, voffA);
;             PG8_WAIT_V(8); PG8_WAIT_L(0); PG8_BAR; PG8_MMA(0, 0, At, B0); PG8_MMA(0, 1, At, B1); PG8_BAR; PG8_SCHED;
;             PG8_LDA(At, 0, 1); PG8_STAGE(PG8_SB(0, 0), b2, voffB); PG8_STAGE(PG8_SB(0, 1), b2 + hstep, voffB); PG8_STAGE(PG8_SA(0, 0), a2, voffA);
;             PG8_WAIT_V(8); PG8_WAIT_L(0); PG8_BAR; PG8_MMA(1, 0, At, B0); PG8_MMA(1, 1, At, B1); PG8_BAR; PG8_SCHED;
.Lew_join_298_0:
	s_waitcnt lgkmcnt(0)
	s_barrier
	s_setprio 1
	s_waitcnt lgkmcnt(0)
	v_mfma_f32_16x16x32_bf16 v[136:139], v[64:67], v[174:177], v[136:139]
	v_mfma_f32_16x16x32_bf16 v[136:139], v[68:71], v[178:181], v[136:139]
	v_mfma_f32_16x16x32_bf16 v[132:135], v[72:75], v[174:177], v[132:135]
	v_mfma_f32_16x16x32_bf16 v[132:135], v[146:149], v[178:181], v[132:135]
	v_mfma_f32_16x16x32_bf16 v[120:123], v[64:67], v[182:185], v[120:123]
	v_mfma_f32_16x16x32_bf16 v[120:123], v[68:71], v[194:197], v[120:123]
	v_mfma_f32_16x16x32_bf16 v[116:119], v[72:75], v[182:185], v[116:119]
	v_mfma_f32_16x16x32_bf16 v[116:119], v[146:149], v[194:197], v[116:119]
	v_mfma_f32_16x16x32_bf16 v[104:107], v[64:67], v[198:201], v[104:107]
	v_mfma_f32_16x16x32_bf16 v[104:107], v[68:71], v[202:205], v[104:107]
	v_mfma_f32_16x16x32_bf16 v[100:103], v[72:75], v[198:201], v[100:103]
	v_mfma_f32_16x16x32_bf16 v[100:103], v[146:149], v[202:205], v[100:103]
	v_mfma_f32_16x16x32_bf16 v[88:91], v[64:67], v[206:209], v[88:91]
	v_mfma_f32_16x16x32_bf16 v[88:91], v[68:71], v[210:213], v[88:91]
	v_mfma_f32_16x16x32_bf16 v[84:87], v[72:75], v[206:209], v[84:87]
	v_mfma_f32_16x16x32_bf16 v[84:87], v[146:149], v[210:213], v[84:87]
	s_setprio 0
	s_setprio 1
	v_mfma_f32_16x16x32_bf16 v[128:131], v[150:153], v[174:177], v[128:131]
	v_mfma_f32_16x16x32_bf16 v[128:131], v[154:157], v[178:181], v[128:131]
	v_mfma_f32_16x16x32_bf16 v[124:127], v[158:161], v[174:177], v[124:127]
	v_mfma_f32_16x16x32_bf16 v[124:127], v[170:173], v[178:181], v[124:127]
	v_mfma_f32_16x16x32_bf16 v[112:115], v[150:153], v[182:185], v[112:115]
	v_mfma_f32_16x16x32_bf16 v[112:115], v[154:157], v[194:197], v[112:115]
	v_mfma_f32_16x16x32_bf16 v[108:111], v[158:161], v[182:185], v[108:111]
	v_mfma_f32_16x16x32_bf16 v[108:111], v[170:173], v[194:197], v[108:111]
	v_mfma_f32_16x16x32_bf16 v[96:99], v[150:153], v[198:201], v[96:99]
	v_mfma_f32_16x16x32_bf16 v[96:99], v[154:157], v[202:205], v[96:99]
	v_mfma_f32_16x16x32_bf16 v[92:95], v[158:161], v[198:201], v[92:95]
	v_mfma_f32_16x16x32_bf16 v[92:95], v[170:173], v[202:205], v[92:95]
	v_mfma_f32_16x16x32_bf16 v[80:83], v[150:153], v[206:209], v[80:83]
	v_mfma_f32_16x16x32_bf16 v[80:83], v[154:157], v[210:213], v[80:83]
	v_mfma_f32_16x16x32_bf16 v[76:79], v[158:161], v[206:209], v[76:79]
	v_mfma_f32_16x16x32_bf16 v[76:79], v[170:173], v[210:213], v[76:79]
	s_setprio 0
	s_barrier
	s_add_i32 s36, s38, s87
	s_mov_b32 m0, s36
	ds_read_b128 v[174:177], v169 offset:16384
	ds_read_b128 v[178:181], v169 offset:17408
	ds_read_b128 v[182:185], v169 offset:18432
	ds_read_b128 v[194:197], v169 offset:19456
	ds_read_b128 v[198:201], v169 offset:20480
	ds_read_b128 v[202:205], v169 offset:21504
	ds_read_b128 v[206:209], v169 offset:22528
	ds_read_b128 v[210:213], v169 offset:23552
	global_load_lds_dwordx4 v188, s[68:69]
	s_add_i32 m0, s36, 0x2000
	s_add_u32 s36, s68, 0x80000
	s_addc_u32 s37, s69, 0
	s_add_i32 s38, s39, s87
	global_load_lds_dwordx4 v140, s[68:69]
	s_mov_b32 m0, s38
	s_nop 0
	global_load_lds_dwordx4 v188, s[36:37]
	s_add_i32 m0, s38, 0x2000
	s_nop 0
	global_load_lds_dwordx4 v140, s[36:37]
	s_mov_b32 m0, s88
	s_nop 0
	global_load_lds_dwordx4 v188, s[70:71]
	s_mov_b32 m0, s89
	s_nop 0
	global_load_lds_dwordx4 v140, s[70:71]
	s_cmp_eq_u32 s95, -2
	s_cbranch_scc1 .Lew_first_298_1
	s_waitcnt vmcnt(8)
.Lew_join_298_1:
	s_waitcnt lgkmcnt(0)
	s_barrier
	s_setprio 1
	s_waitcnt lgkmcnt(0)
	v_mfma_f32_16x16x32_bf16 v[56:59], v[64:67], v[174:177], v[56:59]
	v_mfma_f32_16x16x32_bf16 v[56:59], v[68:71], v[178:181], v[56:59]
	v_mfma_f32_16x16x32_bf16 v[60:63], v[72:75], v[174:177], v[60:63]
	v_mfma_f32_16x16x32_bf16 v[60:63], v[146:149], v[178:181], v[60:63]
	v_mfma_f32_16x16x32_bf16 v[40:43], v[64:67], v[182:185], v[40:43]
	v_mfma_f32_16x16x32_bf16 v[40:43], v[68:71], v[194:197], v[40:43]
	v_mfma_f32_16x16x32_bf16 v[44:47], v[72:75], v[182:185], v[44:47]
	v_mfma_f32_16x16x32_bf16 v[44:47], v[146:149], v[194:197], v[44:47]
	v_mfma_f32_16x16x32_bf16 v[24:27], v[64:67], v[198:201], v[24:27]
	v_mfma_f32_16x16x32_bf16 v[24:27], v[68:71], v[202:205], v[24:27]
	v_mfma_f32_16x16x32_bf16 v[28:31], v[72:75], v[198:201], v[28:31]
	v_mfma_f32_16x16x32_bf16 v[28:31], v[146:149], v[202:205], v[28:31]
	v_mfma_f32_16x16x32_bf16 v[8:11], v[64:67], v[206:209], v[8:11]
	v_mfma_f32_16x16x32_bf16 v[8:11], v[68:71], v[210:213], v[8:11]
	v_mfma_f32_16x16x32_bf16 v[12:15], v[72:75], v[206:209], v[12:15]
	v_mfma_f32_16x16x32_bf16 v[12:15], v[146:149], v[210:213], v[12:15]
	s_setprio 0
	s_setprio 1
	v_mfma_f32_16x16x32_bf16 v[52:55], v[150:153], v[174:177], v[52:55]
	v_mfma_f32_16x16x32_bf16 v[52:55], v[154:157], v[178:181], v[52:55]
	v_mfma_f32_16x16x32_bf16 v[48:51], v[158:161], v[174:177], v[48:51]
	v_mfma_f32_16x16x32_bf16 v[48:51], v[170:173], v[178:181], v[48:51]
	v_mfma_f32_16x16x32_bf16 v[36:39], v[150:153], v[182:185], v[36:39]
	v_mfma_f32_16x16x32_bf16 v[36:39], v[154:157], v[194:197], v[36:39]
	v_mfma_f32_16x16x32_bf16 v[32:35], v[158:161], v[182:185], v[32:35]
	v_mfma_f32_16x16x32_bf16 v[32:35], v[170:173], v[194:197], v[32:35]
	v_mfma_f32_16x16x32_bf16 v[20:23], v[150:153], v[198:201], v[20:23]
	v_mfma_f32_16x16x32_bf16 v[20:23], v[154:157], v[202:205], v[20:23]
	v_mfma_f32_16x16x32_bf16 v[16:19], v[158:161], v[198:201], v[16:19]
	v_mfma_f32_16x16x32_bf16 v[16:19], v[170:173], v[202:205], v[16:19]
	v_mfma_f32_16x16x32_bf16 v[4:7], v[150:153], v[206:209], v[4:7]
	v_mfma_f32_16x16x32_bf16 v[4:7], v[154:157], v[210:213], v[4:7]
	v_mfma_f32_16x16x32_bf16 v[0:3], v[158:161], v[206:209], v[0:3]
	v_mfma_f32_16x16x32_bf16 v[0:3], v[170:173], v[210:213], v[0:3]
	s_setprio 0
	s_barrier
; #define PG8_STAGE(bufoff, gbase, voff) do { _Pragma("unroll") for (int _i = 0; _i < 2; ++_i) \
;         __builtin_amdgcn_global_load_lds((const unsigned*)((const char*)(gbase) + (voff)[_i]), (PG8_LAS unsigned*)(lds + (bufoff) + ldsw + _i * 8192), 16, 0, 0); } while (0)
; #define PG8_LDA(dst, b, h) do { _Pragma("unroll") for (int m = 0; m < 4; ++m) _Pragma("unroll") for (int k = 0; k < 2; ++k) dst[m][k] = *(const PG8_LAS bf16x8*)(lds + PG8_SA(b, h) + aoff + m * 2048 + k * 1024); } while (0)
; #define PG8_LDB(dst, b, h) do { _Pragma("unroll") for (int n = 0; n < 2; ++n) _Pragma("unroll") for (int k = 0; k < 2; ++k) dst[n][k] = *(const PG8_LAS bf16x8*)(lds + PG8_SB(b, h) + boff + n * 2048 + k * 1024); } while (0)
; #define PG8_MMA(ai, bj, At, Bt) do { __builtin_amdgcn_s_setprio(1); _Pragma("unroll") for (int m = 0; m < 4; ++m) _Pragma("unroll") for (int n = 0; n < 2; ++n) _Pragma("unroll") for (int k = 0; k < 2; ++k) \
;         acc[ai][bj][m][n] = __builtin_amdgcn_mfma_f32_16x16x32_bf16(Bt[n][k], At[m][k], acc[ai][bj][m][n], 0, 0, 0); __builtin_amdgcn_s_setprio(0); } while (0)
; #define PG8_WAIT_V(n) asm volatile("s_waitcnt vmcnt(" #n ")" ::: "memory")
; #define PG8_WAIT_L(n) asm volatile("s_waitcnt lgkmcnt(" #n ")" ::: "memory")
; #define PG8_BAR __builtin_amdgcn_s_barrier()
; #define PG8_SCHED __builtin_amdgcn_sched_barrier(0)
; template <class Epi, class Sched, bool ALIGN_EPI = false, bool SP2 = false>
; __device__ __forceinline__ void gemm_phase(PG8_LAS unsigned char* lds, const Gemm g, const Sched& S, const Epi& E) {
;     ...
;         for (int t = 0; t < nt; t += 2) {
;     ...
;             PG8_LDB(B0, 1, 0); PG8_LDB(B1, 1, 1); PG8_SCHED; PG8_LDA(At, 1, 0); PG8_STAGE(PG8_SA(0, 1), a2 + hstep, voffA);
;             PG8_WAIT_V(8); PG8_WAIT_L(0); PG8_BAR; PG8_MMA(0, 0, At, B0); PG8_MMA(0, 1, At, B1); PG8_BAR; PG8_SCHED;
;             PG8_LDA(At, 1, 1); PG8_STAGE(PG8_SB(1, 0), b3, voffB); PG8_STAGE(PG8_SB(1, 1), b3 + hstep, voffB); PG8_STAGE(PG8_SA(1, 0), a3, voffA);
;             PG8_WAIT_V(8); PG8_WAIT_L(0); PG8_BAR; PG8_MMA(1, 0, At, B0); PG8_MMA(1, 1, At, B1); PG8_BAR; PG8_SCHED;
	s_add_i32 s38, 0, 0x18000
	s_add_i32 s39, 0, 0x1c000
	ds_read_b128 v[64:67], v214 offset:32768
	ds_read_b128 v[68:71], v214 offset:33792
	ds_read_b128 v[72:75], v214 offset:34816
	ds_read_b128 v[146:149], v214 offset:35840
	ds_read_b128 v[150:153], v214 offset:49152
	ds_read_b128 v[154:157], v214 offset:50176
	ds_read_b128 v[158:161], v214 offset:51200
	ds_read_b128 v[170:173], v214 offset:52224
	s_add_u32 s36, s70, 0x80000
	s_addc_u32 s37, s71, 0
	s_mov_b32 m0, s14
	ds_read_b128 v[174:177], v169 offset:32768
	ds_read_b128 v[178:181], v169 offset:33792
	ds_read_b128 v[182:185], v169 offset:34816
	ds_read_b128 v[194:197], v169 offset:35840
	ds_read_b128 v[198:201], v169 offset:36864
	ds_read_b128 v[202:205], v169 offset:37888
	ds_read_b128 v[206:209], v169 offset:38912
	ds_read_b128 v[210:213], v169 offset:39936
	global_load_lds_dwordx4 v188, s[36:37]
	s_mov_b32 m0, s15
	s_nop 0
	global_load_lds_dwordx4 v140, s[36:37]
	s_waitcnt vmcnt(8)
	s_waitcnt lgkmcnt(0)
	s_barrier
	s_setprio 1
	s_waitcnt lgkmcnt(0)
	v_mfma_f32_16x16x32_bf16 v[136:139], v[64:67], v[174:177], v[136:139]
	v_mfma_f32_16x16x32_bf16 v[136:139], v[68:71], v[178:181], v[136:139]
	v_mfma_f32_16x16x32_bf16 v[132:135], v[72:75], v[174:177], v[132:135]
	v_mfma_f32_16x16x32_bf16 v[132:135], v[146:149], v[178:181], v[132:135]
	v_mfma_f32_16x16x32_bf16 v[120:123], v[64:67], v[182:185], v[120:123]
	v_mfma_f32_16x16x32_bf16 v[120:123], v[68:71], v[194:197], v[120:123]
	v_mfma_f32_16x16x32_bf16 v[116:119], v[72:75], v[182:185], v[116:119]
	v_mfma_f32_16x16x32_bf16 v[116:119], v[146:149], v[194:197], v[116:119]
	v_mfma_f32_16x16x32_bf16 v[104:107], v[64:67], v[198:201], v[104:107]
	v_mfma_f32_16x16x32_bf16 v[104:107], v[68:71], v[202:205], v[104:107]
	v_mfma_f32_16x16x32_bf16 v[100:103], v[72:75], v[198:201], v[100:103]
	v_mfma_f32_16x16x32_bf16 v[100:103], v[146:149], v[202:205], v[100:103]
	v_mfma_f32_16x16x32_bf16 v[88:91], v[64:67], v[206:209], v[88:91]
	v_mfma_f32_16x16x32_bf16 v[88:91], v[68:71], v[210:213], v[88:91]
	v_mfma_f32_16x16x32_bf16 v[84:87], v[72:75], v[206:209], v[84:87]
	v_mfma_f32_16x16x32_bf16 v[84:87], v[146:149], v[210:213], v[84:87]
	s_setprio 0
	s_setprio 1
	v_mfma_f32_16x16x32_bf16 v[128:131], v[150:153], v[174:177], v[128:131]
	v_mfma_f32_16x16x32_bf16 v[128:131], v[154:157], v[178:181], v[128:131]
	v_mfma_f32_16x16x32_bf16 v[124:127], v[158:161], v[174:177], v[124:127]
	v_mfma_f32_16x16x32_bf16 v[124:127], v[170:173], v[178:181], v[124:127]
	v_mfma_f32_16x16x32_bf16 v[112:115], v[150:153], v[182:185], v[112:115]
	v_mfma_f32_16x16x32_bf16 v[112:115], v[154:157], v[194:197], v[112:115]
	v_mfma_f32_16x16x32_bf16 v[108:111], v[158:161], v[182:185], v[108:111]
	v_mfma_f32_16x16x32_bf16 v[108:111], v[170:173], v[194:197], v[108:111]
	v_mfma_f32_16x16x32_bf16 v[96:99], v[150:153], v[198:201], v[96:99]
	v_mfma_f32_16x16x32_bf16 v[96:99], v[154:157], v[202:205], v[96:99]
	v_mfma_f32_16x16x32_bf16 v[92:95], v[158:161], v[198:201], v[92:95]
	v_mfma_f32_16x16x32_bf16 v[92:95], v[170:173], v[202:205], v[92:95]
	v_mfma_f32_16x16x32_bf16 v[80:83], v[150:153], v[206:209], v[80:83]
	v_mfma_f32_16x16x32_bf16 v[80:83], v[154:157], v[210:213], v[80:83]
	v_mfma_f32_16x16x32_bf16 v[76:79], v[158:161], v[206:209], v[76:79]
	v_mfma_f32_16x16x32_bf16 v[76:79], v[170:173], v[210:213], v[76:79]
	s_setprio 0
	s_barrier
	s_add_i32 s36, s38, s87
	s_mov_b32 m0, s36
	ds_read_b128 v[174:177], v169 offset:49152
	ds_read_b128 v[178:181], v169 offset:50176
	ds_read_b128 v[182:185], v169 offset:51200
	ds_read_b128 v[194:197], v169 offset:52224
	ds_read_b128 v[198:201], v169 offset:53248
	ds_read_b128 v[202:205], v169 offset:54272
	ds_read_b128 v[206:209], v169 offset:55296
	ds_read_b128 v[210:213], v169 offset:56320
	s_add_u32 s100, s68, 0x80
	s_addc_u32 s101, s69, 0
	global_load_lds_dwordx4 v188, s[100:101]
	s_add_i32 m0, s36, 0x2000
	s_add_u32 s36, s68, 0x80080
	s_addc_u32 s37, s69, 0
	s_add_i32 s38, s39, s87
	global_load_lds_dwordx4 v140, s[100:101]
	s_mov_b32 m0, s38
	s_nop 0
	global_load_lds_dwordx4 v188, s[36:37]
	s_add_i32 m0, s38, 0x2000
	s_nop 0
	global_load_lds_dwordx4 v140, s[36:37]
	s_mov_b32 m0, s81
	s_nop 0
	s_add_u32 s100, s70, 0x80
	s_addc_u32 s101, s71, 0
	global_load_lds_dwordx4 v188, s[100:101]
	s_mov_b32 m0, s80
	s_nop 0
	global_load_lds_dwordx4 v140, s[100:101]
	s_waitcnt vmcnt(8)
	s_waitcnt lgkmcnt(0)
	s_barrier
	s_setprio 1
	s_waitcnt lgkmcnt(0)
	v_mfma_f32_16x16x32_bf16 v[56:59], v[64:67], v[174:177], v[56:59]
	v_mfma_f32_16x16x32_bf16 v[56:59], v[68:71], v[178:181], v[56:59]
	v_mfma_f32_16x16x32_bf16 v[60:63], v[72:75], v[174:177], v[60:63]
	v_mfma_f32_16x16x32_bf16 v[60:63], v[146:149], v[178:181], v[60:63]
	v_mfma_f32_16x16x32_bf16 v[40:43], v[64:67], v[182:185], v[40:43]
	v_mfma_f32_16x16x32_bf16 v[40:43], v[68:71], v[194:197], v[40:43]
	v_mfma_f32_16x16x32_bf16 v[44:47], v[72:75], v[182:185], v[44:47]
	v_mfma_f32_16x16x32_bf16 v[44:47], v[146:149], v[194:197], v[44:47]
	v_mfma_f32_16x16x32_bf16 v[24:27], v[64:67], v[198:201], v[24:27]
	v_mfma_f32_16x16x32_bf16 v[24:27], v[68:71], v[202:205], v[24:27]
	v_mfma_f32_16x16x32_bf16 v[28:31], v[72:75], v[198:201], v[28:31]
	v_mfma_f32_16x16x32_bf16 v[28:31], v[146:149], v[202:205], v[28:31]
	v_mfma_f32_16x16x32_bf16 v[8:11], v[64:67], v[206:209], v[8:11]
	v_mfma_f32_16x16x32_bf16 v[8:11], v[68:71], v[210:213], v[8:11]
	v_mfma_f32_16x16x32_bf16 v[12:15], v[72:75], v[206:209], v[12:15]
	v_mfma_f32_16x16x32_bf16 v[12:15], v[146:149], v[210:213], v[12:15]
	s_setprio 0
	s_setprio 1
	v_mfma_f32_16x16x32_bf16 v[52:55], v[150:153], v[174:177], v[52:55]
	v_mfma_f32_16x16x32_bf16 v[52:55], v[154:157], v[178:181], v[52:55]
	v_mfma_f32_16x16x32_bf16 v[48:51], v[158:161], v[174:177], v[48:51]
	v_mfma_f32_16x16x32_bf16 v[48:51], v[170:173], v[178:181], v[48:51]
	v_mfma_f32_16x16x32_bf16 v[36:39], v[150:153], v[182:185], v[36:39]
	v_mfma_f32_16x16x32_bf16 v[36:39], v[154:157], v[194:197], v[36:39]
	v_mfma_f32_16x16x32_bf16 v[32:35], v[158:161], v[182:185], v[32:35]
	v_mfma_f32_16x16x32_bf16 v[32:35], v[170:173], v[194:197], v[32:35]
	v_mfma_f32_16x16x32_bf16 v[20:23], v[150:153], v[198:201], v[20:23]
	v_mfma_f32_16x16x32_bf16 v[20:23], v[154:157], v[202:205], v[20:23]
	v_mfma_f32_16x16x32_bf16 v[16:19], v[158:161], v[198:201], v[16:19]
	v_mfma_f32_16x16x32_bf16 v[16:19], v[170:173], v[202:205], v[16:19]
	v_mfma_f32_16x16x32_bf16 v[4:7], v[150:153], v[206:209], v[4:7]
	v_mfma_f32_16x16x32_bf16 v[4:7], v[154:157], v[210:213], v[4:7]
	v_mfma_f32_16x16x32_bf16 v[0:3], v[158:161], v[206:209], v[0:3]
	v_mfma_f32_16x16x32_bf16 v[0:3], v[170:173], v[210:213], v[0:3]
	s_setprio 0
	s_barrier
	s_add_i32 s95, s95, 2
	s_add_u32 vcc_lo, vcc_lo, 0x100
	s_addc_u32 vcc_hi, vcc_hi, 0
	s_add_u32 s3, s3, 0x100
	s_addc_u32 s94, s94, 0
	s_cmp_gt_u32 s95, 29
	s_cbranch_scc0 .LBB0_298
	s_and_b64 vcc, exec, s[58:59]
	s_cbranch_vccz .LBB0_301
	s_barrier

; #define PG8_STAGE(bufoff, gbase, voff) do { _Pragma("unroll") for (int _i = 0; _i < 2; ++_i) \
;         __builtin_amdgcn_global_load_lds((const unsigned*)((const char*)(gbase) + (voff)[_i]), (PG8_LAS unsigned*)(lds + (bufoff) + ldsw + _i * 8192), 16, 0, 0); } while (0)
; #define PG8_WAIT_V(n) asm volatile("s_waitcnt vmcnt(" #n ")" ::: "memory")
; #define PG8_BAR __builtin_amdgcn_s_barrier()
; template <class Epi, class Sched, bool ALIGN_EPI = false, bool SP2 = false>
; __device__ __forceinline__ void gemm_phase(PG8_LAS unsigned char* lds, const Gemm g, const Sched& S, const Epi& E) {
;     ...
;         PG8_STAGE(PG8_SB(0, 0), cB, voffB); PG8_STAGE(PG8_SB(0, 1), cB + hstep, voffB); PG8_STAGE(PG8_SA(0, 0), cA, voffA); PG8_STAGE(PG8_SA(0, 1), cA + hstep, voffA);
;         if (wr == 1) PG8_BAR;
;         PG8_WAIT_V(2); PG8_BAR;
;         PG8_STAGE(PG8_SB(1, 0), cB + kstep, voffB); PG8_STAGE(PG8_SA(1, 0), cA + kstep, voffA); PG8_STAGE(PG8_SB(1, 1), cB + hstep + kstep, voffB);
;         PG8_WAIT_V(6); PG8_BAR;
.LBB0_334:
	s_and_b32 s7, s4, 3
	s_add_i32 m0, s53, 0x18000
	v_lshl_add_u64 v[6:7], v[6:7], 0, s[90:91]
	s_lshl_b32 s75, s5, 6
	s_lshl_b32 s12, s5, 13
	s_lshl_b32 s13, s7, 12
	s_waitcnt vmcnt(2)
	s_barrier
	global_load_lds_dwordx4 v[6:7], off
	v_lshl_add_u64 v[4:5], v[4:5], 0, s[90:91]
	s_add_i32 m0, s53, 0x1a000
	s_add_i32 s76, s53, 0x8000
	s_add_i32 s77, s53, 0xa000
	global_load_lds_dwordx4 v[4:5], off
	v_lshl_add_u64 v[0:1], v[0:1], 0, s[90:91]
	s_mov_b32 m0, s76
	s_add_u32 s4, s10, 0x80080
	global_load_lds_dwordx4 v[0:1], off
	v_lshl_add_u64 v[0:1], v[2:3], 0, s[90:91]
	s_mov_b32 m0, s77
	s_addc_u32 s5, s11, 0
	global_load_lds_dwordx4 v[0:1], off
	s_add_i32 m0, s53, 0x1c000
	v_lshl_add_u64 v[0:1], s[4:5], 0, v[160:161]
	global_load_lds_dwordx4 v[0:1], off
	v_lshl_add_u64 v[0:1], s[4:5], 0, v[162:163]
	s_add_i32 m0, s53, 0x1e000
	v_and_b32_e32 v165, 15, v8
	global_load_lds_dwordx4 v[0:1], off
	v_bfe_u32 v0, v8, 4, 2
	v_lshlrev_b32_e32 v1, 3, v0
	v_lshlrev_b32_e32 v188, 4, v0
	v_lshlrev_b32_e32 v0, 2, v0
	v_lshl_or_b32 v166, s7, 4, v0
	v_lshlrev_b32_e32 v0, 15, v9
	v_and_b32_e32 v0, 0xffff0000, v0
	v_lshl_or_b32 v164, s7, 5, v1
	v_lshl_add_u32 v0, v10, 12, v0
	v_and_b32_e32 v1, 1, v9
	v_lshlrev_b32_e32 v3, 2, v8
	v_lshl_or_b32 v0, v1, 6, v0
	v_lshl_or_b32 v2, v165, 6, v188
	v_and_b32_e32 v3, 32, v3
	s_cmpk_lt_u32 s3, 0x100
	v_lshl_add_u32 v170, v11, 1, v0
	v_lshlrev_b32_e32 v0, 15, v12
	v_bitop3_b32 v4, v2, s12, v3 bitop3:0xde
	v_bitop3_b32 v167, v2, s13, v3 bitop3:0xde
	s_cselect_b64 s[12:13], -1, 0
	s_waitcnt lgkmcnt(0)
	s_ashr_i32 s78, s74, 31
	s_lshl_b32 s3, s7, 6
	v_readlane_b32 s4, v254, 0
	v_and_b32_e32 v0, 0xffff0000, v0
	s_waitcnt vmcnt(0)
	v_readlane_b32 s5, v254, 1
	s_add_u32 s4, s4, s3
	v_lshl_add_u32 v0, v13, 12, v0
	v_and_b32_e32 v1, 1, v12
	s_addc_u32 s5, s5, 0
	v_lshl_or_b32 v0, v1, 6, v0
	v_lshl_add_u64 v[168:169], s[4:5], 0, v[188:189]
	v_mov_b32_e32 v171, v189
	v_lshl_add_u32 v172, v14, 1, v0
	v_mov_b32_e32 v173, v189
	s_mov_b32 s79, 0
	v_add_u32_e32 v204, 0, v4
	s_movk_i32 s41, 0x6000
	s_movk_i32 s42, 0x2000
	s_movk_i32 s43, 0x7cf
	s_mov_b64 s[38:39], 0x400
	s_barrier
	s_branch .LBB0_337

; #define PG8_STAGE(bufoff, gbase, voff) do { _Pragma("unroll") for (int _i = 0; _i < 2; ++_i) \
;         __builtin_amdgcn_global_load_lds((const unsigned*)((const char*)(gbase) + (voff)[_i]), (PG8_LAS unsigned*)(lds + (bufoff) + ldsw + _i * 8192), 16, 0, 0); } while (0)
; #define PG8_LDA(dst, b, h) do { _Pragma("unroll") for (int m = 0; m < 4; ++m) _Pragma("unroll") for (int k = 0; k < 2; ++k) dst[m][k] = *(const PG8_LAS bf16x8*)(lds + PG8_SA(b, h) + aoff + m * 2048 + k * 1024); } while (0)
; #define PG8_LDB(dst, b, h) do { _Pragma("unroll") for (int n = 0; n < 2; ++n) _Pragma("unroll") for (int k = 0; k < 2; ++k) dst[n][k] = *(const PG8_LAS bf16x8*)(lds + PG8_SB(b, h) + boff + n * 2048 + k * 1024); } while (0)
; #define PG8_WAIT_V(n) asm volatile("s_waitcnt vmcnt(" #n ")" ::: "memory")
; #define PG8_WAIT_L(n) asm volatile("s_waitcnt lgkmcnt(" #n ")" ::: "memory")
; #define PG8_BAR __builtin_amdgcn_s_barrier()
; template <class Epi, class Sched, bool ALIGN_EPI = false, bool SP2 = false>
; __device__ __forceinline__ void gemm_phase(PG8_LAS unsigned char* lds, const Gemm g, const Sched& S, const Epi& E) {
;     ...
;         const bool has_next = S.next(ui + 1, nxt);
;         const char* nA = has_next ? (const char*)g.A + (size_t)nxt.pm * tstep : cA; const char* nB = has_next ? (const char*)g.Bt + (size_t)nxt.pn * tstep : cB;
;         for (int t = 0; t < nt; t += 2) {
;             const bool last = (t == nt - 2);
;             const char* a1 = cA + (size_t)(t + 1) * kstep;
;             const char* a2 = last ? nA : cA + (size_t)(t + 2) * kstep; const char* b2 = last ? nB : cB + (size_t)(t + 2) * kstep;
;             const char* a3 = a2 + kstep; const char* b3 = b2 + kstep;
;             if (last && has_next) S.a_ready(nxt);
;             if constexpr (SP2) {
;             PG8_LDB(B0, 0, 0); PG8_LDB(B1, 0, 1); PG8_SCHED; PG8_LDA(At, 0, 0); PG8_STAGE(PG8_SA(1, 1), a1 + hstep, voffA);
;             PG8_WAIT_V(8); PG8_WAIT_L(0); PG8_BAR; PG8_MMA(0, 0, At, B0); PG8_MMA(0, 1, At, B1); PG8_BAR; PG8_SCHED;
;     ...
; #pragma unroll
;         for (int a = 0; a < 2; ++a)
; #pragma unroll
;             for (int b = 0; b < 2; ++b)
; #pragma unroll
;                 for (int m = 0; m < 4; ++m)
; #pragma unroll
;                     for (int n = 0; n < 2; ++n) acc[a][b][m][n] = (f32x4){0.f, 0.f, 0.f, 0.f};
;         cur = nxt; cA = nA; cB = nB; ++ui;
.LBB0_343:
	s_ashr_i32 s57, s56, 31
	s_lshl_b64 s[14:15], s[56:57], 20
	s_add_u32 s44, s34, s14
	s_addc_u32 s45, s35, s15
	s_and_b64 s[14:15], s[4:5], exec
	s_cselect_b32 s7, s45, s9
	s_cselect_b32 s14, s44, s8
	s_ashr_i32 s61, s60, 31
	s_lshl_b64 s[54:55], s[60:61], 20
	s_add_u32 s58, s68, s54
	s_addc_u32 s59, s69, s55
	s_and_b64 s[54:55], s[4:5], exec
	s_cselect_b32 s15, s59, s11
	s_cselect_b32 s54, s58, s10
	s_add_u32 s8, s8, 0x80080
	s_addc_u32 s9, s9, 0
	s_add_u32 s55, s10, 0x100
	v_mov_b32_e32 v0, 0
	s_addc_u32 s3, s11, 0
	s_mov_b32 s57, -2
	v_mov_b32_e32 v1, v0
	v_mov_b32_e32 v2, v0
	v_mov_b32_e32 v3, v0
	v_mov_b32_e32 v4, v0
	v_mov_b32_e32 v5, v0
	v_mov_b32_e32 v6, v0
	v_mov_b32_e32 v7, v0
	v_mov_b32_e32 v16, v0
	v_mov_b32_e32 v17, v0
	v_mov_b32_e32 v18, v0
	v_mov_b32_e32 v19, v0
	v_mov_b32_e32 v20, v0
	v_mov_b32_e32 v21, v0
	v_mov_b32_e32 v22, v0
	v_mov_b32_e32 v23, v0
	v_mov_b32_e32 v32, v0
	v_mov_b32_e32 v33, v0
	v_mov_b32_e32 v34, v0
	v_mov_b32_e32 v35, v0
	v_mov_b32_e32 v36, v0
	v_mov_b32_e32 v37, v0
	v_mov_b32_e32 v38, v0
	v_mov_b32_e32 v39, v0
	v_mov_b32_e32 v48, v0
	v_mov_b32_e32 v49, v0
	v_mov_b32_e32 v50, v0
	v_mov_b32_e32 v51, v0
	v_mov_b32_e32 v52, v0
	v_mov_b32_e32 v53, v0
	v_mov_b32_e32 v54, v0
	v_mov_b32_e32 v55, v0
	v_mov_b32_e32 v8, v0
	v_mov_b32_e32 v9, v0
	v_mov_b32_e32 v10, v0
	v_mov_b32_e32 v11, v0
	v_mov_b32_e32 v12, v0
	v_mov_b32_e32 v13, v0
	v_mov_b32_e32 v14, v0
	v_mov_b32_e32 v15, v0
	v_mov_b32_e32 v24, v0
	v_mov_b32_e32 v25, v0
	v_mov_b32_e32 v26, v0
	v_mov_b32_e32 v27, v0
	v_mov_b32_e32 v28, v0
	v_mov_b32_e32 v29, v0
	v_mov_b32_e32 v30, v0
	v_mov_b32_e32 v31, v0
	v_mov_b32_e32 v40, v0
	v_mov_b32_e32 v41, v0
	v_mov_b32_e32 v42, v0
	v_mov_b32_e32 v43, v0
	v_mov_b32_e32 v44, v0
	v_mov_b32_e32 v45, v0
	v_mov_b32_e32 v46, v0
	v_mov_b32_e32 v47, v0
	v_mov_b32_e32 v56, v0
	v_mov_b32_e32 v57, v0
	v_mov_b32_e32 v58, v0
	v_mov_b32_e32 v59, v0
	v_mov_b32_e32 v60, v0
	v_mov_b32_e32 v61, v0
	v_mov_b32_e32 v62, v0
	v_mov_b32_e32 v63, v0
	v_mov_b32_e32 v64, v0
	v_mov_b32_e32 v65, v0
	v_mov_b32_e32 v66, v0
	v_mov_b32_e32 v67, v0
	s_nop 0
	v_mov_b32_e32 v68, v0
	v_mov_b32_e32 v69, v0
	v_mov_b32_e32 v70, v0
	v_mov_b32_e32 v71, v0
	v_mov_b32_e32 v80, v0
	v_mov_b32_e32 v81, v0
	v_mov_b32_e32 v82, v0
	v_mov_b32_e32 v83, v0
	v_mov_b32_e32 v84, v0
	v_mov_b32_e32 v85, v0
	v_mov_b32_e32 v86, v0
	v_mov_b32_e32 v87, v0
	v_mov_b32_e32 v96, v0
	v_mov_b32_e32 v97, v0
	v_mov_b32_e32 v98, v0
	v_mov_b32_e32 v99, v0
	v_mov_b32_e32 v100, v0
	v_mov_b32_e32 v101, v0
	v_mov_b32_e32 v102, v0
	v_mov_b32_e32 v103, v0
	v_mov_b32_e32 v112, v0
	v_mov_b32_e32 v113, v0
	v_mov_b32_e32 v114, v0
	v_mov_b32_e32 v115, v0
	v_mov_b32_e32 v116, v0
	v_mov_b32_e32 v117, v0
	v_mov_b32_e32 v118, v0
	v_mov_b32_e32 v119, v0
	v_mov_b32_e32 v72, v0
	v_mov_b32_e32 v73, v0
	v_mov_b32_e32 v74, v0
	v_mov_b32_e32 v75, v0
	v_mov_b32_e32 v76, v0
	v_mov_b32_e32 v77, v0
	v_mov_b32_e32 v78, v0
	v_mov_b32_e32 v79, v0
	v_mov_b32_e32 v88, v0
	v_mov_b32_e32 v89, v0
	v_mov_b32_e32 v90, v0
	v_mov_b32_e32 v91, v0
	v_mov_b32_e32 v92, v0
	v_mov_b32_e32 v93, v0
	v_mov_b32_e32 v94, v0
	v_mov_b32_e32 v95, v0
	v_mov_b32_e32 v104, v0
	v_mov_b32_e32 v105, v0
	v_mov_b32_e32 v106, v0
	v_mov_b32_e32 v107, v0
	v_mov_b32_e32 v108, v0
	v_mov_b32_e32 v109, v0
	v_mov_b32_e32 v110, v0
	v_mov_b32_e32 v111, v0
	v_mov_b32_e32 v120, v0
	v_mov_b32_e32 v121, v0
	v_mov_b32_e32 v122, v0
	v_mov_b32_e32 v123, v0
	v_mov_b32_e32 v124, v0
	v_mov_b32_e32 v125, v0
	v_mov_b32_e32 v126, v0
	v_mov_b32_e32 v127, v0
	s_waitcnt vmcnt(16)
	v_add_u32_e32 v218, 0x10000, v167
.LBB0_344:
	s_add_u32 s10, s8, 0xfff80080
	s_addc_u32 s11, s9, -1
	s_add_i32 s36, 0, 0x10000
	s_cmp_eq_u32 s57, 28
	s_cselect_b32 s63, s7, s11
	s_cselect_b32 s62, s14, s10
	s_cselect_b32 s11, s15, s3
	s_cselect_b32 s10, s54, s55
	s_add_i32 s37, 0, 0x14000
	ds_read_b128 v[128:131], v218
	ds_read_b128 v[132:135], v218 offset:1024
	ds_read_b128 v[136:139], v218 offset:2048
	ds_read_b128 v[140:143], v218 offset:3072
	ds_read_b128 v[144:147], v218 offset:16384
	ds_read_b128 v[148:151], v218 offset:17408
	ds_read_b128 v[152:155], v218 offset:18432
	ds_read_b128 v[156:159], v218 offset:19456
	s_add_i32 m0, s53, 0xc000
	ds_read_b128 v[174:177], v204
	ds_read_b128 v[178:181], v204 offset:1024
	ds_read_b128 v[182:185], v204 offset:2048
	ds_read_b128 v[194:197], v204 offset:3072
	ds_read_b128 v[198:201], v204 offset:4096
	ds_read_b128 v[206:209], v204 offset:5120
	ds_read_b128 v[210:213], v204 offset:6144
	ds_read_b128 v[214:217], v204 offset:7168
	global_load_lds_dwordx4 v170, s[8:9]
	s_add_i32 m0, s53, 0xe000
	s_nop 0
	global_load_lds_dwordx4 v172, s[8:9]
	s_cmp_eq_u32 s57, -2
	s_cbranch_scc1 .Lew_first_344_0
	s_waitcnt vmcnt(8)
; #define PG8_STAGE(bufoff, gbase, voff) do { _Pragma("unroll") for (int _i = 0; _i < 2; ++_i) \
;         __builtin_amdgcn_global_load_lds((const unsigned*)((const char*)(gbase) + (voff)[_i]), (PG8_LAS unsigned*)(lds + (bufoff) + ldsw + _i * 8192), 16, 0, 0); } while (0)
; #define PG8_LDA(dst, b, h) do { _Pragma("unroll") for (int m = 0; m < 4; ++m) _Pragma("unroll") for (int k = 0; k < 2; ++k) dst[m][k] = *(const PG8_LAS bf16x8*)(lds + PG8_SA(b, h) + aoff + m * 2048 + k * 1024); } while (0)
; #define PG8_LDB(dst, b, h) do { _Pragma("unroll") for (int n = 0; n < 2; ++n) _Pragma("unroll") for (int k = 0; k < 2; ++k) dst[n][k] = *(const PG8_LAS bf16x8*)(lds + PG8_SB(b, h) + boff + n * 2048 + k * 1024); } while (0)
; #define PG8_MMA(ai, bj, At, Bt) do { __builtin_amdgcn_s_setprio(1); _Pragma("unroll") for (int m = 0; m < 4; ++m) _Pragma("unroll") for (int n = 0; n < 2; ++n) _Pragma("unroll") for (int k = 0; k < 2; ++k) \
;         acc[ai][bj][m][n] = __builtin_amdgcn_mfma_f32_16x16x32_bf16(Bt[n][k], At[m][k], acc[ai][bj][m][n], 0, 0, 0); __builtin_amdgcn_s_setprio(0); } while (0)
; #define PG8_WAIT_V(n) asm volatile("s_waitcnt vmcnt(" #n ")" ::: "memory")
; #define PG8_WAIT_L(n) asm volatile("s_waitcnt lgkmcnt(" #n ")" ::: "memory")
; #define PG8_BAR __builtin_amdgcn_s_barrier()
; #define PG8_SCHED __builtin_amdgcn_sched_barrier(0)
; template <class Epi, class Sched, bool ALIGN_EPI = false, bool SP2 = false>
; __device__ __forceinline__ void gemm_phase(PG8_LAS unsigned char* lds, const Gemm g, const Sched& S, const Epi& E) {
;     ...
;             PG8_LDB(B0, 0, 0); PG8_LDB(B1, 0, 1); PG8_SCHED; PG8_LDA(At, 0, 0); PG8_STAGE(PG8_SA(1, 1), a1 + hstep, voffA);
;             PG8_WAIT_V(8); PG8_WAIT_L(0); PG8_BAR; PG8_MMA(0, 0, At, B0); PG8_MMA(0, 1, At, B1); PG8_BAR; PG8_SCHED;
;             PG8_LDA(At, 0, 1); PG8_STAGE(PG8_SB(0, 0), b2, voffB); PG8_STAGE(PG8_SB(0, 1), b2 + hstep, voffB); PG8_STAGE(PG8_SA(0, 0), a2, voffA);
;             PG8_WAIT_V(8); PG8_WAIT_L(0); PG8_BAR; PG8_MMA(1, 0, At, B0); PG8_MMA(1, 1, At, B1); PG8_BAR; PG8_SCHED;
.Lew_join_344_0:
	s_waitcnt lgkmcnt(0)
	s_barrier
	s_setprio 1
	s_waitcnt lgkmcnt(0)
	v_mfma_f32_16x16x32_bf16 v[124:127], v[128:131], v[174:177], v[124:127]
	v_mfma_f32_16x16x32_bf16 v[124:127], v[132:135], v[178:181], v[124:127]
	v_mfma_f32_16x16x32_bf16 v[120:123], v[136:139], v[174:177], v[120:123]
	v_mfma_f32_16x16x32_bf16 v[120:123], v[140:143], v[178:181], v[120:123]
	v_mfma_f32_16x16x32_bf16 v[108:111], v[128:131], v[182:185], v[108:111]
	v_mfma_f32_16x16x32_bf16 v[108:111], v[132:135], v[194:197], v[108:111]
	v_mfma_f32_16x16x32_bf16 v[104:107], v[136:139], v[182:185], v[104:107]
	v_mfma_f32_16x16x32_bf16 v[104:107], v[140:143], v[194:197], v[104:107]
	v_mfma_f32_16x16x32_bf16 v[92:95], v[128:131], v[198:201], v[92:95]
	v_mfma_f32_16x16x32_bf16 v[92:95], v[132:135], v[206:209], v[92:95]
	v_mfma_f32_16x16x32_bf16 v[88:91], v[136:139], v[198:201], v[88:91]
	v_mfma_f32_16x16x32_bf16 v[88:91], v[140:143], v[206:209], v[88:91]
	v_mfma_f32_16x16x32_bf16 v[76:79], v[128:131], v[210:213], v[76:79]
	v_mfma_f32_16x16x32_bf16 v[76:79], v[132:135], v[214:217], v[76:79]
	v_mfma_f32_16x16x32_bf16 v[72:75], v[136:139], v[210:213], v[72:75]
	v_mfma_f32_16x16x32_bf16 v[72:75], v[140:143], v[214:217], v[72:75]
	s_setprio 0
	s_setprio 1
	v_mfma_f32_16x16x32_bf16 v[116:119], v[144:147], v[174:177], v[116:119]
	v_mfma_f32_16x16x32_bf16 v[116:119], v[148:151], v[178:181], v[116:119]
	v_mfma_f32_16x16x32_bf16 v[112:115], v[152:155], v[174:177], v[112:115]
	v_mfma_f32_16x16x32_bf16 v[112:115], v[156:159], v[178:181], v[112:115]
	v_mfma_f32_16x16x32_bf16 v[100:103], v[144:147], v[182:185], v[100:103]
	v_mfma_f32_16x16x32_bf16 v[100:103], v[148:151], v[194:197], v[100:103]
	v_mfma_f32_16x16x32_bf16 v[96:99], v[152:155], v[182:185], v[96:99]
	v_mfma_f32_16x16x32_bf16 v[96:99], v[156:159], v[194:197], v[96:99]
	v_mfma_f32_16x16x32_bf16 v[84:87], v[144:147], v[198:201], v[84:87]
	v_mfma_f32_16x16x32_bf16 v[84:87], v[148:151], v[206:209], v[84:87]
	v_mfma_f32_16x16x32_bf16 v[80:83], v[152:155], v[198:201], v[80:83]
	v_mfma_f32_16x16x32_bf16 v[80:83], v[156:159], v[206:209], v[80:83]
	v_mfma_f32_16x16x32_bf16 v[68:71], v[144:147], v[210:213], v[68:71]
	v_mfma_f32_16x16x32_bf16 v[68:71], v[148:151], v[214:217], v[68:71]
	v_mfma_f32_16x16x32_bf16 v[64:67], v[152:155], v[210:213], v[64:67]
	v_mfma_f32_16x16x32_bf16 v[64:67], v[156:159], v[214:217], v[64:67]
	s_setprio 0
	s_barrier
	s_add_i32 s36, s36, s70
	s_mov_b32 m0, s36
	ds_read_b128 v[174:177], v204 offset:16384
	ds_read_b128 v[178:181], v204 offset:17408
	ds_read_b128 v[182:185], v204 offset:18432
	ds_read_b128 v[194:197], v204 offset:19456
	ds_read_b128 v[198:201], v204 offset:20480
	ds_read_b128 v[206:209], v204 offset:21504
	ds_read_b128 v[210:213], v204 offset:22528
	ds_read_b128 v[214:217], v204 offset:23552
	global_load_lds_dwordx4 v160, s[10:11]
	s_add_i32 m0, s36, 0x2000
	s_add_u32 s64, s10, 0x80000
	s_addc_u32 s65, s11, 0
	s_add_i32 s36, s37, s70
	global_load_lds_dwordx4 v162, s[10:11]
	s_mov_b32 m0, s36
	s_nop 0
	global_load_lds_dwordx4 v160, s[64:65]
	s_add_i32 m0, s36, 0x2000
	s_nop 0
	global_load_lds_dwordx4 v162, s[64:65]
	s_mov_b32 m0, s53
	s_nop 0
	global_load_lds_dwordx4 v160, s[62:63]
	s_mov_b32 m0, s71
	s_nop 0
	global_load_lds_dwordx4 v162, s[62:63]
	s_cmp_eq_u32 s57, -2
	s_cbranch_scc1 .Lew_first_344_1
	s_waitcnt vmcnt(8)
.Lew_join_344_1:
	s_waitcnt lgkmcnt(0)
	s_barrier
	s_setprio 1
	s_waitcnt lgkmcnt(0)
	v_mfma_f32_16x16x32_bf16 v[60:63], v[128:131], v[174:177], v[60:63]
	v_mfma_f32_16x16x32_bf16 v[60:63], v[132:135], v[178:181], v[60:63]
	v_mfma_f32_16x16x32_bf16 v[56:59], v[136:139], v[174:177], v[56:59]
	v_mfma_f32_16x16x32_bf16 v[56:59], v[140:143], v[178:181], v[56:59]
	v_mfma_f32_16x16x32_bf16 v[44:47], v[128:131], v[182:185], v[44:47]
	v_mfma_f32_16x16x32_bf16 v[44:47], v[132:135], v[194:197], v[44:47]
	v_mfma_f32_16x16x32_bf16 v[40:43], v[136:139], v[182:185], v[40:43]
	v_mfma_f32_16x16x32_bf16 v[40:43], v[140:143], v[194:197], v[40:43]
	v_mfma_f32_16x16x32_bf16 v[28:31], v[128:131], v[198:201], v[28:31]
	v_mfma_f32_16x16x32_bf16 v[28:31], v[132:135], v[206:209], v[28:31]
	v_mfma_f32_16x16x32_bf16 v[24:27], v[136:139], v[198:201], v[24:27]
	v_mfma_f32_16x16x32_bf16 v[24:27], v[140:143], v[206:209], v[24:27]
	v_mfma_f32_16x16x32_bf16 v[12:15], v[128:131], v[210:213], v[12:15]
	v_mfma_f32_16x16x32_bf16 v[12:15], v[132:135], v[214:217], v[12:15]
	v_mfma_f32_16x16x32_bf16 v[8:11], v[136:139], v[210:213], v[8:11]
	v_mfma_f32_16x16x32_bf16 v[8:11], v[140:143], v[214:217], v[8:11]
	s_setprio 0
	s_setprio 1
	v_mfma_f32_16x16x32_bf16 v[52:55], v[144:147], v[174:177], v[52:55]
	v_mfma_f32_16x16x32_bf16 v[52:55], v[148:151], v[178:181], v[52:55]
	v_mfma_f32_16x16x32_bf16 v[48:51], v[152:155], v[174:177], v[48:51]
	v_mfma_f32_16x16x32_bf16 v[48:51], v[156:159], v[178:181], v[48:51]
	v_mfma_f32_16x16x32_bf16 v[36:39], v[144:147], v[182:185], v[36:39]
	v_mfma_f32_16x16x32_bf16 v[36:39], v[148:151], v[194:197], v[36:39]
	v_mfma_f32_16x16x32_bf16 v[32:35], v[152:155], v[182:185], v[32:35]
	v_mfma_f32_16x16x32_bf16 v[32:35], v[156:159], v[194:197], v[32:35]
	v_mfma_f32_16x16x32_bf16 v[20:23], v[144:147], v[198:201], v[20:23]
	v_mfma_f32_16x16x32_bf16 v[20:23], v[148:151], v[206:209], v[20:23]
	v_mfma_f32_16x16x32_bf16 v[16:19], v[152:155], v[198:201], v[16:19]
	v_mfma_f32_16x16x32_bf16 v[16:19], v[156:159], v[206:209], v[16:19]
	v_mfma_f32_16x16x32_bf16 v[4:7], v[144:147], v[210:213], v[4:7]
	v_mfma_f32_16x16x32_bf16 v[4:7], v[148:151], v[214:217], v[4:7]
	v_mfma_f32_16x16x32_bf16 v[0:3], v[152:155], v[210:213], v[0:3]
	v_mfma_f32_16x16x32_bf16 v[0:3], v[156:159], v[214:217], v[0:3]
	s_setprio 0
	s_barrier
; #define PG8_STAGE(bufoff, gbase, voff) do { _Pragma("unroll") for (int _i = 0; _i < 2; ++_i) \
;         __builtin_amdgcn_global_load_lds((const unsigned*)((const char*)(gbase) + (voff)[_i]), (PG8_LAS unsigned*)(lds + (bufoff) + ldsw + _i * 8192), 16, 0, 0); } while (0)
; #define PG8_LDA(dst, b, h) do { _Pragma("unroll") for (int m = 0; m < 4; ++m) _Pragma("unroll") for (int k = 0; k < 2; ++k) dst[m][k] = *(const PG8_LAS bf16x8*)(lds + PG8_SA(b, h) + aoff + m * 2048 + k * 1024); } while (0)
; #define PG8_LDB(dst, b, h) do { _Pragma("unroll") for (int n = 0; n < 2; ++n) _Pragma("unroll") for (int k = 0; k < 2; ++k) dst[n][k] = *(const PG8_LAS bf16x8*)(lds + PG8_SB(b, h) + boff + n * 2048 + k * 1024); } while (0)
; #define PG8_MMA(ai, bj, At, Bt) do { __builtin_amdgcn_s_setprio(1); _Pragma("unroll") for (int m = 0; m < 4; ++m) _Pragma("unroll") for (int n = 0; n < 2; ++n) _Pragma("unroll") for (int k = 0; k < 2; ++k) \
;         acc[ai][bj][m][n] = __builtin_amdgcn_mfma_f32_16x16x32_bf16(Bt[n][k], At[m][k], acc[ai][bj][m][n], 0, 0, 0); __builtin_amdgcn_s_setprio(0); } while (0)
; #define PG8_WAIT_V(n) asm volatile("s_waitcnt vmcnt(" #n ")" ::: "memory")
; #define PG8_WAIT_L(n) asm volatile("s_waitcnt lgkmcnt(" #n ")" ::: "memory")
; #define PG8_BAR __builtin_amdgcn_s_barrier()
; #define PG8_SCHED __builtin_amdgcn_sched_barrier(0)
; template <class Epi, class Sched, bool ALIGN_EPI = false, bool SP2 = false>
; __device__ __forceinline__ void gemm_phase(PG8_LAS unsigned char* lds, const Gemm g, const Sched& S, const Epi& E) {
;     ...
;             PG8_LDB(B0, 1, 0); PG8_LDB(B1, 1, 1); PG8_SCHED; PG8_LDA(At, 1, 0); PG8_STAGE(PG8_SA(0, 1), a2 + hstep, voffA);
;             PG8_WAIT_V(8); PG8_WAIT_L(0); PG8_BAR; PG8_MMA(0, 0, At, B0); PG8_MMA(0, 1, At, B1); PG8_BAR; PG8_SCHED;
;             PG8_LDA(At, 1, 1); PG8_STAGE(PG8_SB(1, 0), b3, voffB); PG8_STAGE(PG8_SB(1, 1), b3 + hstep, voffB); PG8_STAGE(PG8_SA(1, 0), a3, voffA);
;             PG8_WAIT_V(8); PG8_WAIT_L(0); PG8_BAR; PG8_MMA(1, 0, At, B0); PG8_MMA(1, 1, At, B1); PG8_BAR; PG8_SCHED;
;     ...
;         if constexpr (ALIGN_EPI) { if (wr == 0) PG8_BAR; }
	s_add_i32 s36, 0, 0x18000
	s_add_i32 s37, 0, 0x1c000
	ds_read_b128 v[128:131], v218 offset:32768
	ds_read_b128 v[132:135], v218 offset:33792
	ds_read_b128 v[136:139], v218 offset:34816
	ds_read_b128 v[140:143], v218 offset:35840
	ds_read_b128 v[144:147], v218 offset:49152
	ds_read_b128 v[148:151], v218 offset:50176
	ds_read_b128 v[152:155], v218 offset:51200
	ds_read_b128 v[156:159], v218 offset:52224
	s_add_u32 s62, s62, 0x80000
	s_addc_u32 s63, s63, 0
	s_mov_b32 m0, s72
	ds_read_b128 v[174:177], v204 offset:32768
	ds_read_b128 v[178:181], v204 offset:33792
	ds_read_b128 v[182:185], v204 offset:34816
	ds_read_b128 v[194:197], v204 offset:35840
	ds_read_b128 v[198:201], v204 offset:36864
	ds_read_b128 v[206:209], v204 offset:37888
	ds_read_b128 v[210:213], v204 offset:38912
	ds_read_b128 v[214:217], v204 offset:39936
	global_load_lds_dwordx4 v160, s[62:63]
	s_mov_b32 m0, s73
	s_nop 0
	global_load_lds_dwordx4 v162, s[62:63]
	s_waitcnt vmcnt(8)
	s_waitcnt lgkmcnt(0)
	s_barrier
	s_setprio 1
	s_waitcnt lgkmcnt(0)
	v_mfma_f32_16x16x32_bf16 v[124:127], v[128:131], v[174:177], v[124:127]
	v_mfma_f32_16x16x32_bf16 v[124:127], v[132:135], v[178:181], v[124:127]
	v_mfma_f32_16x16x32_bf16 v[120:123], v[136:139], v[174:177], v[120:123]
	v_mfma_f32_16x16x32_bf16 v[120:123], v[140:143], v[178:181], v[120:123]
	v_mfma_f32_16x16x32_bf16 v[108:111], v[128:131], v[182:185], v[108:111]
	v_mfma_f32_16x16x32_bf16 v[108:111], v[132:135], v[194:197], v[108:111]
	v_mfma_f32_16x16x32_bf16 v[104:107], v[136:139], v[182:185], v[104:107]
	v_mfma_f32_16x16x32_bf16 v[104:107], v[140:143], v[194:197], v[104:107]
	v_mfma_f32_16x16x32_bf16 v[92:95], v[128:131], v[198:201], v[92:95]
	v_mfma_f32_16x16x32_bf16 v[92:95], v[132:135], v[206:209], v[92:95]
	v_mfma_f32_16x16x32_bf16 v[88:91], v[136:139], v[198:201], v[88:91]
	v_mfma_f32_16x16x32_bf16 v[88:91], v[140:143], v[206:209], v[88:91]
	v_mfma_f32_16x16x32_bf16 v[76:79], v[128:131], v[210:213], v[76:79]
	v_mfma_f32_16x16x32_bf16 v[76:79], v[132:135], v[214:217], v[76:79]
	v_mfma_f32_16x16x32_bf16 v[72:75], v[136:139], v[210:213], v[72:75]
	v_mfma_f32_16x16x32_bf16 v[72:75], v[140:143], v[214:217], v[72:75]
	s_setprio 0
	s_setprio 1
	v_mfma_f32_16x16x32_bf16 v[116:119], v[144:147], v[174:177], v[116:119]
	v_mfma_f32_16x16x32_bf16 v[116:119], v[148:151], v[178:181], v[116:119]
	v_mfma_f32_16x16x32_bf16 v[112:115], v[152:155], v[174:177], v[112:115]
	v_mfma_f32_16x16x32_bf16 v[112:115], v[156:159], v[178:181], v[112:115]
	v_mfma_f32_16x16x32_bf16 v[100:103], v[144:147], v[182:185], v[100:103]
	v_mfma_f32_16x16x32_bf16 v[100:103], v[148:151], v[194:197], v[100:103]
	v_mfma_f32_16x16x32_bf16 v[96:99], v[152:155], v[182:185], v[96:99]
	v_mfma_f32_16x16x32_bf16 v[96:99], v[156:159], v[194:197], v[96:99]
	v_mfma_f32_16x16x32_bf16 v[84:87], v[144:147], v[198:201], v[84:87]
	v_mfma_f32_16x16x32_bf16 v[84:87], v[148:151], v[206:209], v[84:87]
	v_mfma_f32_16x16x32_bf16 v[80:83], v[152:155], v[198:201], v[80:83]
	v_mfma_f32_16x16x32_bf16 v[80:83], v[156:159], v[206:209], v[80:83]
	v_mfma_f32_16x16x32_bf16 v[68:71], v[144:147], v[210:213], v[68:71]
	v_mfma_f32_16x16x32_bf16 v[68:71], v[148:151], v[214:217], v[68:71]
	v_mfma_f32_16x16x32_bf16 v[64:67], v[152:155], v[210:213], v[64:67]
	v_mfma_f32_16x16x32_bf16 v[64:67], v[156:159], v[214:217], v[64:67]
	s_setprio 0
	s_barrier
	s_add_i32 s36, s36, s70
	s_mov_b32 m0, s36
	ds_read_b128 v[174:177], v204 offset:49152
	ds_read_b128 v[178:181], v204 offset:50176
	ds_read_b128 v[182:185], v204 offset:51200
	ds_read_b128 v[194:197], v204 offset:52224
	ds_read_b128 v[198:201], v204 offset:53248
	ds_read_b128 v[206:209], v204 offset:54272
	ds_read_b128 v[210:213], v204 offset:55296
	ds_read_b128 v[214:217], v204 offset:56320
	s_add_u32 s100, s10, 0x80
	s_addc_u32 s101, s11, 0
	global_load_lds_dwordx4 v160, s[100:101]
	s_add_i32 m0, s36, 0x2000
	s_add_u32 s10, s10, 0x80080
	s_addc_u32 s11, s11, 0
	s_add_i32 s36, s37, s70
	s_add_u32 s100, s10, 0xfff80000
	s_addc_u32 s101, s11, -1
	global_load_lds_dwordx4 v162, s[100:101]
	s_mov_b32 m0, s36
	s_nop 0
	global_load_lds_dwordx4 v160, s[10:11]
	s_add_i32 m0, s36, 0x2000
	s_nop 0
	global_load_lds_dwordx4 v162, s[10:11]
	s_mov_b32 m0, s76
	s_nop 0
	s_add_u32 s100, s62, 0xfff80080
	s_addc_u32 s101, s63, -1
	global_load_lds_dwordx4 v160, s[100:101]
	s_mov_b32 m0, s77
	s_nop 0
	global_load_lds_dwordx4 v162, s[100:101]
	s_waitcnt vmcnt(8)
	s_waitcnt lgkmcnt(0)
	s_barrier
	s_setprio 1
	s_waitcnt lgkmcnt(0)
	v_mfma_f32_16x16x32_bf16 v[60:63], v[128:131], v[174:177], v[60:63]
	v_mfma_f32_16x16x32_bf16 v[60:63], v[132:135], v[178:181], v[60:63]
	v_mfma_f32_16x16x32_bf16 v[56:59], v[136:139], v[174:177], v[56:59]
	v_mfma_f32_16x16x32_bf16 v[56:59], v[140:143], v[178:181], v[56:59]
	v_mfma_f32_16x16x32_bf16 v[44:47], v[128:131], v[182:185], v[44:47]
	v_mfma_f32_16x16x32_bf16 v[44:47], v[132:135], v[194:197], v[44:47]
	v_mfma_f32_16x16x32_bf16 v[40:43], v[136:139], v[182:185], v[40:43]
	v_mfma_f32_16x16x32_bf16 v[40:43], v[140:143], v[194:197], v[40:43]
	v_mfma_f32_16x16x32_bf16 v[28:31], v[128:131], v[198:201], v[28:31]
	v_mfma_f32_16x16x32_bf16 v[28:31], v[132:135], v[206:209], v[28:31]
	v_mfma_f32_16x16x32_bf16 v[24:27], v[136:139], v[198:201], v[24:27]
	v_mfma_f32_16x16x32_bf16 v[24:27], v[140:143], v[206:209], v[24:27]
	v_mfma_f32_16x16x32_bf16 v[12:15], v[128:131], v[210:213], v[12:15]
	v_mfma_f32_16x16x32_bf16 v[12:15], v[132:135], v[214:217], v[12:15]
	v_mfma_f32_16x16x32_bf16 v[8:11], v[136:139], v[210:213], v[8:11]
	v_mfma_f32_16x16x32_bf16 v[8:11], v[140:143], v[214:217], v[8:11]
	s_setprio 0
	s_setprio 1
	v_mfma_f32_16x16x32_bf16 v[52:55], v[144:147], v[174:177], v[52:55]
	v_mfma_f32_16x16x32_bf16 v[52:55], v[148:151], v[178:181], v[52:55]
	v_mfma_f32_16x16x32_bf16 v[48:51], v[152:155], v[174:177], v[48:51]
	v_mfma_f32_16x16x32_bf16 v[48:51], v[156:159], v[178:181], v[48:51]
	v_mfma_f32_16x16x32_bf16 v[36:39], v[144:147], v[182:185], v[36:39]
	v_mfma_f32_16x16x32_bf16 v[36:39], v[148:151], v[194:197], v[36:39]
	v_mfma_f32_16x16x32_bf16 v[32:35], v[152:155], v[182:185], v[32:35]
	v_mfma_f32_16x16x32_bf16 v[32:35], v[156:159], v[194:197], v[32:35]
	v_mfma_f32_16x16x32_bf16 v[20:23], v[144:147], v[198:201], v[20:23]
	v_mfma_f32_16x16x32_bf16 v[20:23], v[148:151], v[206:209], v[20:23]
	v_mfma_f32_16x16x32_bf16 v[16:19], v[152:155], v[198:201], v[16:19]
	v_mfma_f32_16x16x32_bf16 v[16:19], v[156:159], v[206:209], v[16:19]
	v_mfma_f32_16x16x32_bf16 v[4:7], v[144:147], v[210:213], v[4:7]
	v_mfma_f32_16x16x32_bf16 v[4:7], v[148:151], v[214:217], v[4:7]
	v_mfma_f32_16x16x32_bf16 v[0:3], v[152:155], v[210:213], v[0:3]
	v_mfma_f32_16x16x32_bf16 v[0:3], v[156:159], v[214:217], v[0:3]
	s_setprio 0
	s_barrier
	s_add_i32 s57, s57, 2
	s_add_u32 s8, s8, 0x100
	s_addc_u32 s9, s9, 0
	s_add_u32 s55, s55, 0x100
	s_addc_u32 s3, s3, 0
	s_cmp_gt_u32 s57, 29
	s_cbranch_scc0 .LBB0_344
	s_and_b64 vcc, exec, s[12:13]
	s_cbranch_vccz .LBB0_347
	s_barrier
